# K-loop load steps: issue the LDS-DMA stage loads before the ds_reads (more DMA flight time) in swiglu/proj/act/gate loops
# speedup vs baseline: 1.0081x; 1.0023x over previous
; #define PG8_STAGE(bufoff, gbase, voff) do { _Pragma("unroll") for (int _i = 0; _i < 2; ++_i) \
;         __builtin_amdgcn_global_load_lds((const unsigned*)((const char*)(gbase) + (voff)[_i]), (LAS unsigned*)(lds + (bufoff) + ldsw + _i * 8192), 16, 0, 0); } while (0)
; #define PG8_LDA(dst, b, h) do { _Pragma("unroll") for (int m = 0; m < 4; ++m) _Pragma("unroll") for (int k = 0; k < 2; ++k) dst[m][k] = *(const LAS bf16x8*)(lds + PG8_SA(b, h) + aoff + m * 2048 + k * 1024); } while (0)
; #define PG8_LDB(dst, b, h) do { _Pragma("unroll") for (int n = 0; n < 2; ++n) _Pragma("unroll") for (int k = 0; k < 2; ++k) dst[n][k] = *(const LAS bf16x8*)(lds + PG8_SB(b, h) + boff + n * 2048 + k * 1024); } while (0)
; #define PG8_MMA(ai, bj, At, Bt) do { __builtin_amdgcn_s_setprio(1); _Pragma("unroll") for (int m = 0; m < 4; ++m) _Pragma("unroll") for (int n = 0; n < 2; ++n) _Pragma("unroll") for (int k = 0; k < 2; ++k) \
;         acc[ai][bj][m][n] = __builtin_amdgcn_mfma_f32_16x16x32_bf16(Bt[n][k], At[m][k], acc[ai][bj][m][n], 0, 0, 0); __builtin_amdgcn_s_setprio(0); } while (0)
; #define PG8_WAIT_V(n) asm volatile("s_waitcnt vmcnt(" #n ")" ::: "memory")
; #define PG8_WAIT_L(n) asm volatile("s_waitcnt lgkmcnt(" #n ")" ::: "memory")
; template <class Epi>
; __device__ __forceinline__ void gemm_phase(LAS unsigned char* lds, const Gemm g, const Sched& S, const Epi& E) {
;     ...
;         for (int t = 0; t < nt; t += 2) {
;             const bool last = (t == nt - 2);
;             const char* a1 = cA + (size_t)(t + 1) * kstep;
;             const char* a2 = last ? nA : cA + (size_t)(t + 2) * kstep; const char* b2 = last ? nB : cB + (size_t)(t + 2) * kstep;
;             const char* a3 = a2 + kstep; const char* b3 = b2 + kstep;
;             PG8_LDB(B0, 0, 0); PG8_SCHED; PG8_LDA(At, 0, 0); PG8_STAGE(PG8_SA(1, 1), a1 + hstepA, voffA);
;             PG8_WAIT_L(8); PG8_BAR; PG8_WAIT_L(0); PG8_MMA(0, 0, At, B0); PG8_BAR; PG8_SCHED;
;             PG8_LDB(B1, 0, 1); PG8_STAGE(PG8_SB(0, 0), b2, voffB);
;             PG8_BAR; PG8_WAIT_L(0); PG8_MMA(0, 1, At, B1); PG8_BAR;
;             PG8_LDA(At, 0, 1); PG8_STAGE(PG8_SA(0, 0), a2, voffA);
;             PG8_BAR; PG8_WAIT_L(0); PG8_MMA(1, 0, At, B0); PG8_BAR; PG8_SCHED;
;             PG8_STAGE(PG8_SB(0, 1), b2 + hstepB, voffB);
;             PG8_WAIT_V(6); PG8_BAR; PG8_MMA(1, 1, At, B1); PG8_BAR;
.Lresync_y_461:
.LBB0_461:
	s_add_i32 s14, s88, 2
	s_add_u32 s8, s4, 0x80
	s_addc_u32 s9, s5, 0
	s_cmp_eq_u32 s42, s88
	s_cselect_b32 s88, s57, s8
	s_cselect_b32 s89, s71, s9
	s_cselect_b32 s91, s59, s35
	s_cselect_b32 s90, s72, s34
	v_lshl_add_u64 v[178:179], s[4:5], 0, v[202:203]
	s_add_i32 m0, s24, 0xc000
	s_nop 0
	global_load_lds_dwordx4 v[178:179], off
	v_lshl_add_u64 v[178:179], s[4:5], 0, v[204:205]
	s_add_i32 m0, s24, 0xe000
	s_nop 0
	global_load_lds_dwordx4 v[178:179], off
	s_add_i32 s15, 0, 0x10000
	v_add_u32_e32 v114, s15, v211
	ds_read_b128 v[82:85], v114
	ds_read_b128 v[94:97], v114 offset:1024
	ds_read_b128 v[98:101], v114 offset:2048
	ds_read_b128 v[114:117], v114 offset:3072
	ds_read_b128 v[122:125], v213
	ds_read_b128 v[130:133], v213 offset:1024
	ds_read_b128 v[146:149], v213 offset:2048
	ds_read_b128 v[150:153], v213 offset:3072
	ds_read_b128 v[162:165], v213 offset:4096
	ds_read_b128 v[166:169], v213 offset:5120
	ds_read_b128 v[170:173], v213 offset:6144
	ds_read_b128 v[174:177], v213 offset:7168
	s_add_i32 s8, 0, 0x14000
	v_add_u32_e32 v190, s8, v211
	ds_read_b128 v[178:181], v190
	ds_read_b128 v[182:185], v190 offset:1024
	ds_read_b128 v[186:189], v190 offset:2048
	ds_read_b128 v[190:193], v190 offset:3072
	s_waitcnt vmcnt(8)
	s_waitcnt lgkmcnt(0)
	v_mfma_f32_16x16x32_bf16 v[158:161], v[82:85], v[122:125], v[158:161]
	v_mfma_f32_16x16x32_bf16 v[154:157], v[98:101], v[122:125], v[154:157]
	v_mfma_f32_16x16x32_bf16 v[134:137], v[82:85], v[146:149], v[134:137]
	v_mfma_f32_16x16x32_bf16 v[126:129], v[98:101], v[146:149], v[126:129]
	s_barrier
	s_setprio 1
	v_mfma_f32_16x16x32_bf16 v[106:109], v[82:85], v[162:165], v[106:109]
	v_mfma_f32_16x16x32_bf16 v[102:105], v[98:101], v[162:165], v[102:105]
	v_mfma_f32_16x16x32_bf16 v[78:81], v[82:85], v[170:173], v[78:81]
	v_mfma_f32_16x16x32_bf16 v[74:77], v[98:101], v[170:173], v[74:77]
	v_mfma_f32_16x16x32_bf16 v[158:161], v[94:97], v[130:133], v[158:161]
	v_mfma_f32_16x16x32_bf16 v[154:157], v[114:117], v[130:133], v[154:157]
	v_mfma_f32_16x16x32_bf16 v[134:137], v[94:97], v[150:153], v[134:137]
	v_mfma_f32_16x16x32_bf16 v[126:129], v[114:117], v[150:153], v[126:129]
	v_mfma_f32_16x16x32_bf16 v[106:109], v[94:97], v[166:169], v[106:109]
	v_mfma_f32_16x16x32_bf16 v[102:105], v[114:117], v[166:169], v[102:105]
	v_mfma_f32_16x16x32_bf16 v[78:81], v[94:97], v[174:177], v[78:81]
	v_mfma_f32_16x16x32_bf16 v[74:77], v[114:117], v[174:177], v[74:77]
	v_mfma_f32_16x16x32_bf16 v[142:145], v[178:181], v[122:125], v[142:145]
	v_mfma_f32_16x16x32_bf16 v[118:121], v[178:181], v[146:149], v[118:121]
	v_mfma_f32_16x16x32_bf16 v[110:113], v[186:189], v[146:149], v[110:113]
	v_mfma_f32_16x16x32_bf16 v[90:93], v[178:181], v[162:165], v[90:93]
	v_mfma_f32_16x16x32_bf16 v[86:89], v[186:189], v[162:165], v[86:89]
	v_mfma_f32_16x16x32_bf16 v[70:73], v[178:181], v[170:173], v[70:73]
	v_mfma_f32_16x16x32_bf16 v[66:69], v[186:189], v[170:173], v[66:69]
	v_mfma_f32_16x16x32_bf16 v[142:145], v[182:185], v[130:133], v[142:145]
	v_mfma_f32_16x16x32_bf16 v[122:125], v[186:189], v[122:125], v[138:141]
	v_mfma_f32_16x16x32_bf16 v[118:121], v[182:185], v[150:153], v[118:121]
	v_mfma_f32_16x16x32_bf16 v[110:113], v[190:193], v[150:153], v[110:113]
	v_mfma_f32_16x16x32_bf16 v[90:93], v[182:185], v[166:169], v[90:93]
	v_mfma_f32_16x16x32_bf16 v[86:89], v[190:193], v[166:169], v[86:89]
	v_mfma_f32_16x16x32_bf16 v[70:73], v[182:185], v[174:177], v[70:73]
	v_mfma_f32_16x16x32_bf16 v[66:69], v[190:193], v[174:177], v[66:69]
	v_mfma_f32_16x16x32_bf16 v[122:125], v[190:193], v[130:133], v[122:125]
	s_setprio 0
	s_barrier
	s_add_i32 s9, s15, s3
	v_lshl_add_u64 v[194:195], s[90:91], 0, v[0:1]
	s_mov_b32 m0, s9
	s_nop 0
	global_load_lds_dwordx4 v[194:195], off
	v_lshl_add_u64 v[206:207], s[90:91], 0, v[200:201]
	s_add_i32 m0, s9, 0x2000
	s_nop 0
	global_load_lds_dwordx4 v[206:207], off
	s_mov_b32 m0, s24
	v_lshl_add_u64 v[208:209], s[88:89], 0, v[196:197]
	global_load_lds_dwordx4 v[208:209], off
	v_lshl_add_u64 v[214:215], s[88:89], 0, v[198:199]
	s_mov_b32 m0, s33
	s_nop 0
	global_load_lds_dwordx4 v[214:215], off
	s_add_u32 s90, s90, s78
	s_addc_u32 s91, s91, s79
	s_add_i32 s8, s8, s3
	v_lshl_add_u64 v[216:217], s[90:91], 0, v[0:1]
	s_mov_b32 m0, s8
	v_lshl_add_u64 v[222:223], s[90:91], 0, v[200:201]
	global_load_lds_dwordx4 v[216:217], off
	s_add_i32 m0, s8, 0x2000
	s_nop 0
	global_load_lds_dwordx4 v[222:223], off
	ds_read_b128 v[130:133], v213 offset:16384
	ds_read_b128 v[138:141], v213 offset:17408
	ds_read_b128 v[146:149], v213 offset:18432
	ds_read_b128 v[150:153], v213 offset:19456
	ds_read_b128 v[162:165], v213 offset:20480
	ds_read_b128 v[166:169], v213 offset:21504
	ds_read_b128 v[170:173], v213 offset:22528
	ds_read_b128 v[174:177], v213 offset:23552
	s_waitcnt vmcnt(8)
	s_waitcnt lgkmcnt(0)
	v_mfma_f32_16x16x32_bf16 v[62:65], v[82:85], v[130:133], v[62:65]
	v_mfma_f32_16x16x32_bf16 v[58:61], v[98:101], v[130:133], v[58:61]
	v_mfma_f32_16x16x32_bf16 v[46:49], v[82:85], v[146:149], v[46:49]
	v_mfma_f32_16x16x32_bf16 v[42:45], v[98:101], v[146:149], v[42:45]
	s_barrier
; #define PG8_STAGE(bufoff, gbase, voff) do { _Pragma("unroll") for (int _i = 0; _i < 2; ++_i) \
;         __builtin_amdgcn_global_load_lds((const unsigned*)((const char*)(gbase) + (voff)[_i]), (LAS unsigned*)(lds + (bufoff) + ldsw + _i * 8192), 16, 0, 0); } while (0)
; #define PG8_LDA(dst, b, h) do { _Pragma("unroll") for (int m = 0; m < 4; ++m) _Pragma("unroll") for (int k = 0; k < 2; ++k) dst[m][k] = *(const LAS bf16x8*)(lds + PG8_SA(b, h) + aoff + m * 2048 + k * 1024); } while (0)
; #define PG8_LDB(dst, b, h) do { _Pragma("unroll") for (int n = 0; n < 2; ++n) _Pragma("unroll") for (int k = 0; k < 2; ++k) dst[n][k] = *(const LAS bf16x8*)(lds + PG8_SB(b, h) + boff + n * 2048 + k * 1024); } while (0)
; #define PG8_MMA(ai, bj, At, Bt) do { __builtin_amdgcn_s_setprio(1); _Pragma("unroll") for (int m = 0; m < 4; ++m) _Pragma("unroll") for (int n = 0; n < 2; ++n) _Pragma("unroll") for (int k = 0; k < 2; ++k) \
;         acc[ai][bj][m][n] = __builtin_amdgcn_mfma_f32_16x16x32_bf16(Bt[n][k], At[m][k], acc[ai][bj][m][n], 0, 0, 0); __builtin_amdgcn_s_setprio(0); } while (0)
; #define PG8_WAIT_V(n) asm volatile("s_waitcnt vmcnt(" #n ")" ::: "memory")
; #define PG8_WAIT_L(n) asm volatile("s_waitcnt lgkmcnt(" #n ")" ::: "memory")
; #define PG8_BAR __builtin_amdgcn_s_barrier()
; #define PG8_SCHED __builtin_amdgcn_sched_barrier(0)
; template <class Epi>
; __device__ __forceinline__ void gemm_phase(LAS unsigned char* lds, const Gemm g, const Sched& S, const Epi& E) {
;     ...
;             PG8_BAR; PG8_WAIT_L(0); PG8_MMA(1, 0, At, B0); PG8_BAR; PG8_SCHED;
;             PG8_STAGE(PG8_SB(0, 1), b2 + hstepB, voffB);
;             PG8_WAIT_V(6); PG8_BAR; PG8_MMA(1, 1, At, B1); PG8_BAR;
;             PG8_LDB(B0, 1, 0); PG8_SCHED; PG8_LDA(At, 1, 0); PG8_STAGE(PG8_SA(0, 1), a2 + hstepA, voffA);
;             PG8_WAIT_L(8); PG8_BAR; PG8_WAIT_L(0); PG8_MMA(0, 0, At, B0); PG8_BAR; PG8_SCHED;
;             PG8_LDB(B1, 1, 1); PG8_STAGE(PG8_SB(1, 0), b3, voffB);
;             PG8_BAR; PG8_WAIT_L(0); PG8_MMA(0, 1, At, B1); PG8_BAR;
	s_setprio 1
	v_mfma_f32_16x16x32_bf16 v[30:33], v[82:85], v[162:165], v[30:33]
	v_mfma_f32_16x16x32_bf16 v[26:29], v[98:101], v[162:165], v[26:29]
	v_mfma_f32_16x16x32_bf16 v[14:17], v[82:85], v[170:173], v[14:17]
	v_mfma_f32_16x16x32_bf16 v[10:13], v[98:101], v[170:173], v[10:13]
	v_mfma_f32_16x16x32_bf16 v[62:65], v[94:97], v[138:141], v[62:65]
	v_mfma_f32_16x16x32_bf16 v[58:61], v[114:117], v[138:141], v[58:61]
	v_mfma_f32_16x16x32_bf16 v[46:49], v[94:97], v[150:153], v[46:49]
	v_mfma_f32_16x16x32_bf16 v[42:45], v[114:117], v[150:153], v[42:45]
	v_mfma_f32_16x16x32_bf16 v[30:33], v[94:97], v[166:169], v[30:33]
	v_mfma_f32_16x16x32_bf16 v[26:29], v[114:117], v[166:169], v[26:29]
	v_mfma_f32_16x16x32_bf16 v[14:17], v[94:97], v[174:177], v[14:17]
	v_mfma_f32_16x16x32_bf16 v[10:13], v[114:117], v[174:177], v[10:13]
	v_mfma_f32_16x16x32_bf16 v[54:57], v[178:181], v[130:133], v[54:57]
	v_mfma_f32_16x16x32_bf16 v[50:53], v[186:189], v[130:133], v[50:53]
	v_mfma_f32_16x16x32_bf16 v[38:41], v[178:181], v[146:149], v[38:41]
	v_mfma_f32_16x16x32_bf16 v[34:37], v[186:189], v[146:149], v[34:37]
	v_mfma_f32_16x16x32_bf16 v[22:25], v[178:181], v[162:165], v[22:25]
	v_mfma_f32_16x16x32_bf16 v[18:21], v[186:189], v[162:165], v[18:21]
	v_mfma_f32_16x16x32_bf16 v[6:9], v[178:181], v[170:173], v[6:9]
	v_mfma_f32_16x16x32_bf16 v[2:5], v[186:189], v[170:173], v[2:5]
	v_mfma_f32_16x16x32_bf16 v[54:57], v[182:185], v[138:141], v[54:57]
	v_mfma_f32_16x16x32_bf16 v[50:53], v[190:193], v[138:141], v[50:53]
	v_mfma_f32_16x16x32_bf16 v[38:41], v[182:185], v[150:153], v[38:41]
	v_mfma_f32_16x16x32_bf16 v[34:37], v[190:193], v[150:153], v[34:37]
	v_mfma_f32_16x16x32_bf16 v[22:25], v[182:185], v[166:169], v[22:25]
	v_mfma_f32_16x16x32_bf16 v[18:21], v[190:193], v[166:169], v[18:21]
	v_mfma_f32_16x16x32_bf16 v[6:9], v[182:185], v[174:177], v[6:9]
	v_mfma_f32_16x16x32_bf16 v[2:5], v[190:193], v[174:177], v[2:5]
	s_setprio 0
	s_barrier
	s_add_u32 s88, s88, s36
	s_addc_u32 s89, s89, s37
	s_mov_b32 m0, s38
	v_lshl_add_u64 v[178:179], s[88:89], 0, v[196:197]
	global_load_lds_dwordx4 v[178:179], off
	v_lshl_add_u64 v[178:179], s[88:89], 0, v[198:199]
	s_mov_b32 m0, s39
	s_nop 0
	global_load_lds_dwordx4 v[178:179], off
	s_add_i32 s8, 0, 0x18000
	v_add_u32_e32 v114, s8, v211
	ds_read_b128 v[82:85], v114
	ds_read_b128 v[94:97], v114 offset:1024
	ds_read_b128 v[98:101], v114 offset:2048
	ds_read_b128 v[114:117], v114 offset:3072
	ds_read_b128 v[130:133], v213 offset:32768
	ds_read_b128 v[138:141], v213 offset:33792
	ds_read_b128 v[146:149], v213 offset:34816
	ds_read_b128 v[150:153], v213 offset:35840
	ds_read_b128 v[162:165], v213 offset:36864
	ds_read_b128 v[166:169], v213 offset:37888
	ds_read_b128 v[170:173], v213 offset:38912
	ds_read_b128 v[174:177], v213 offset:39936
	s_add_i32 s9, 0, 0x1c000
	v_add_u32_e32 v190, s9, v211
	ds_read_b128 v[178:181], v190
	ds_read_b128 v[182:185], v190 offset:1024
	ds_read_b128 v[186:189], v190 offset:2048
	ds_read_b128 v[190:193], v190 offset:3072
	s_waitcnt vmcnt(8)
	s_waitcnt lgkmcnt(0)
	v_mfma_f32_16x16x32_bf16 v[158:161], v[82:85], v[130:133], v[158:161]
	v_mfma_f32_16x16x32_bf16 v[154:157], v[98:101], v[130:133], v[154:157]
	v_mfma_f32_16x16x32_bf16 v[134:137], v[82:85], v[146:149], v[134:137]
	v_mfma_f32_16x16x32_bf16 v[126:129], v[98:101], v[146:149], v[126:129]
	s_barrier
	s_setprio 1
	v_mfma_f32_16x16x32_bf16 v[106:109], v[82:85], v[162:165], v[106:109]
	v_mfma_f32_16x16x32_bf16 v[102:105], v[98:101], v[162:165], v[102:105]
	v_mfma_f32_16x16x32_bf16 v[78:81], v[82:85], v[170:173], v[78:81]
	v_mfma_f32_16x16x32_bf16 v[74:77], v[98:101], v[170:173], v[74:77]
	v_mfma_f32_16x16x32_bf16 v[158:161], v[94:97], v[138:141], v[158:161]
	v_mfma_f32_16x16x32_bf16 v[154:157], v[114:117], v[138:141], v[154:157]
	v_mfma_f32_16x16x32_bf16 v[134:137], v[94:97], v[150:153], v[134:137]
	v_mfma_f32_16x16x32_bf16 v[126:129], v[114:117], v[150:153], v[126:129]
	v_mfma_f32_16x16x32_bf16 v[106:109], v[94:97], v[166:169], v[106:109]
	v_mfma_f32_16x16x32_bf16 v[102:105], v[114:117], v[166:169], v[102:105]
	v_mfma_f32_16x16x32_bf16 v[78:81], v[94:97], v[174:177], v[78:81]
	v_mfma_f32_16x16x32_bf16 v[74:77], v[114:117], v[174:177], v[74:77]
	v_mfma_f32_16x16x32_bf16 v[142:145], v[178:181], v[130:133], v[142:145]
	v_mfma_f32_16x16x32_bf16 v[122:125], v[186:189], v[130:133], v[122:125]
	v_mfma_f32_16x16x32_bf16 v[118:121], v[178:181], v[146:149], v[118:121]
	v_mfma_f32_16x16x32_bf16 v[110:113], v[186:189], v[146:149], v[110:113]
	v_mfma_f32_16x16x32_bf16 v[90:93], v[178:181], v[162:165], v[90:93]
	v_mfma_f32_16x16x32_bf16 v[86:89], v[186:189], v[162:165], v[86:89]
	v_mfma_f32_16x16x32_bf16 v[70:73], v[178:181], v[170:173], v[70:73]
	v_mfma_f32_16x16x32_bf16 v[66:69], v[186:189], v[170:173], v[66:69]
	v_mfma_f32_16x16x32_bf16 v[142:145], v[182:185], v[138:141], v[142:145]
	v_mfma_f32_16x16x32_bf16 v[138:141], v[190:193], v[138:141], v[122:125]
	v_mfma_f32_16x16x32_bf16 v[118:121], v[182:185], v[150:153], v[118:121]
	v_mfma_f32_16x16x32_bf16 v[110:113], v[190:193], v[150:153], v[110:113]
	v_mfma_f32_16x16x32_bf16 v[90:93], v[182:185], v[166:169], v[90:93]
	v_mfma_f32_16x16x32_bf16 v[86:89], v[190:193], v[166:169], v[86:89]
	v_mfma_f32_16x16x32_bf16 v[70:73], v[182:185], v[174:177], v[70:73]
	v_mfma_f32_16x16x32_bf16 v[66:69], v[190:193], v[174:177], v[66:69]
	s_setprio 0
	s_barrier
; #define PG8_STAGE(bufoff, gbase, voff) do { _Pragma("unroll") for (int _i = 0; _i < 2; ++_i) \
;         __builtin_amdgcn_global_load_lds((const unsigned*)((const char*)(gbase) + (voff)[_i]), (LAS unsigned*)(lds + (bufoff) + ldsw + _i * 8192), 16, 0, 0); } while (0)
; #define PG8_LDA(dst, b, h) do { _Pragma("unroll") for (int m = 0; m < 4; ++m) _Pragma("unroll") for (int k = 0; k < 2; ++k) dst[m][k] = *(const LAS bf16x8*)(lds + PG8_SA(b, h) + aoff + m * 2048 + k * 1024); } while (0)
; #define PG8_MMA(ai, bj, At, Bt) do { __builtin_amdgcn_s_setprio(1); _Pragma("unroll") for (int m = 0; m < 4; ++m) _Pragma("unroll") for (int n = 0; n < 2; ++n) _Pragma("unroll") for (int k = 0; k < 2; ++k) \
;         acc[ai][bj][m][n] = __builtin_amdgcn_mfma_f32_16x16x32_bf16(Bt[n][k], At[m][k], acc[ai][bj][m][n], 0, 0, 0); __builtin_amdgcn_s_setprio(0); } while (0)
; #define PG8_WAIT_V(n) asm volatile("s_waitcnt vmcnt(" #n ")" ::: "memory")
; #define PG8_WAIT_L(n) asm volatile("s_waitcnt lgkmcnt(" #n ")" ::: "memory")
; #define PG8_BAR __builtin_amdgcn_s_barrier()
; #define PG8_SCHED __builtin_amdgcn_sched_barrier(0)
; template <class Epi>
; __device__ __forceinline__ void gemm_phase(LAS unsigned char* lds, const Gemm g, const Sched& S, const Epi& E) {
;     ...
;             PG8_LDA(At, 1, 1); PG8_STAGE(PG8_SA(1, 0), a3, voffA);
;             PG8_BAR; PG8_WAIT_L(0); PG8_MMA(1, 0, At, B0); PG8_BAR; PG8_SCHED;
;             PG8_STAGE(PG8_SB(1, 1), b3 + hstepB, voffB);
;             PG8_WAIT_V(6); PG8_BAR; PG8_MMA(1, 1, At, B1); PG8_BAR;
;         }
	s_add_i32 s8, s8, s3
	v_lshl_add_u64 v[194:195], v[194:195], 0, s[60:61]
	s_mov_b32 m0, s8
	s_nop 0
	global_load_lds_dwordx4 v[194:195], off
	v_lshl_add_u64 v[194:195], v[206:207], 0, s[60:61]
	s_add_i32 m0, s8, 0x2000
	s_nop 0
	global_load_lds_dwordx4 v[194:195], off
	s_mov_b32 m0, s40
	v_lshl_add_u64 v[194:195], v[208:209], 0, s[60:61]
	global_load_lds_dwordx4 v[194:195], off
	v_lshl_add_u64 v[194:195], v[214:215], 0, s[60:61]
	s_mov_b32 m0, s41
	s_nop 0
	global_load_lds_dwordx4 v[194:195], off
	s_add_i32 s8, s9, s3
	v_lshl_add_u64 v[194:195], v[216:217], 0, s[60:61]
	s_mov_b32 m0, s8
	s_nop 0
	global_load_lds_dwordx4 v[194:195], off
	v_lshl_add_u64 v[194:195], v[222:223], 0, s[60:61]
	s_add_i32 m0, s8, 0x2000
	s_nop 0
	global_load_lds_dwordx4 v[194:195], off
	ds_read_b128 v[122:125], v213 offset:49152
	ds_read_b128 v[130:133], v213 offset:50176
	ds_read_b128 v[146:149], v213 offset:51200
	ds_read_b128 v[150:153], v213 offset:52224
	ds_read_b128 v[162:165], v213 offset:53248
	ds_read_b128 v[166:169], v213 offset:54272
	ds_read_b128 v[170:173], v213 offset:55296
	ds_read_b128 v[174:177], v213 offset:56320
	s_waitcnt vmcnt(8)
	s_waitcnt lgkmcnt(0)
	v_mfma_f32_16x16x32_bf16 v[62:65], v[82:85], v[122:125], v[62:65]
	v_mfma_f32_16x16x32_bf16 v[58:61], v[98:101], v[122:125], v[58:61]
	v_mfma_f32_16x16x32_bf16 v[46:49], v[82:85], v[146:149], v[46:49]
	v_mfma_f32_16x16x32_bf16 v[42:45], v[98:101], v[146:149], v[42:45]
	s_barrier
	s_setprio 1
	v_mfma_f32_16x16x32_bf16 v[30:33], v[82:85], v[162:165], v[30:33]
	v_mfma_f32_16x16x32_bf16 v[26:29], v[98:101], v[162:165], v[26:29]
	v_mfma_f32_16x16x32_bf16 v[14:17], v[82:85], v[170:173], v[14:17]
	v_mfma_f32_16x16x32_bf16 v[10:13], v[98:101], v[170:173], v[10:13]
	v_mfma_f32_16x16x32_bf16 v[62:65], v[94:97], v[130:133], v[62:65]
	v_mfma_f32_16x16x32_bf16 v[58:61], v[114:117], v[130:133], v[58:61]
	v_mfma_f32_16x16x32_bf16 v[46:49], v[94:97], v[150:153], v[46:49]
	v_mfma_f32_16x16x32_bf16 v[42:45], v[114:117], v[150:153], v[42:45]
	v_mfma_f32_16x16x32_bf16 v[30:33], v[94:97], v[166:169], v[30:33]
	v_mfma_f32_16x16x32_bf16 v[26:29], v[114:117], v[166:169], v[26:29]
	v_mfma_f32_16x16x32_bf16 v[14:17], v[94:97], v[174:177], v[14:17]
	v_mfma_f32_16x16x32_bf16 v[10:13], v[114:117], v[174:177], v[10:13]
	v_mfma_f32_16x16x32_bf16 v[54:57], v[178:181], v[122:125], v[54:57]
	v_mfma_f32_16x16x32_bf16 v[50:53], v[186:189], v[122:125], v[50:53]
	v_mfma_f32_16x16x32_bf16 v[38:41], v[178:181], v[146:149], v[38:41]
	v_mfma_f32_16x16x32_bf16 v[34:37], v[186:189], v[146:149], v[34:37]
	v_mfma_f32_16x16x32_bf16 v[22:25], v[178:181], v[162:165], v[22:25]
	v_mfma_f32_16x16x32_bf16 v[18:21], v[186:189], v[162:165], v[18:21]
	v_mfma_f32_16x16x32_bf16 v[6:9], v[178:181], v[170:173], v[6:9]
	v_mfma_f32_16x16x32_bf16 v[2:5], v[186:189], v[170:173], v[2:5]
	v_mfma_f32_16x16x32_bf16 v[54:57], v[182:185], v[130:133], v[54:57]
	v_mfma_f32_16x16x32_bf16 v[50:53], v[190:193], v[130:133], v[50:53]
	v_mfma_f32_16x16x32_bf16 v[38:41], v[182:185], v[150:153], v[38:41]
	v_mfma_f32_16x16x32_bf16 v[34:37], v[190:193], v[150:153], v[34:37]
	v_mfma_f32_16x16x32_bf16 v[22:25], v[182:185], v[166:169], v[22:25]
	v_mfma_f32_16x16x32_bf16 v[18:21], v[190:193], v[166:169], v[18:21]
	v_mfma_f32_16x16x32_bf16 v[6:9], v[182:185], v[174:177], v[6:9]
	v_mfma_f32_16x16x32_bf16 v[2:5], v[190:193], v[174:177], v[2:5]
	s_setprio 0
	s_add_u32 s4, s4, 0x100
	s_addc_u32 s5, s5, 0
	s_add_u32 s34, s34, 0x100
	s_addc_u32 s35, s35, 0
	s_cmp_ge_u32 s14, s73
	s_mov_b32 s88, s14
	s_barrier
	s_cbranch_scc0 .LBB0_461
	v_readfirstlane_b32 s98, v219
	s_nop 1
	s_bitcmp1_b32 s98, 8
	s_cbranch_scc1 .Lresync_x_461
	s_barrier

; #define PG8_STAGE(bufoff, gbase, voff) do { _Pragma("unroll") for (int _i = 0; _i < 2; ++_i) \
;         __builtin_amdgcn_global_load_lds((const unsigned*)((const char*)(gbase) + (voff)[_i]), (LAS unsigned*)(lds + (bufoff) + ldsw + _i * 8192), 16, 0, 0); } while (0)
; #define PG8_LDA(dst, b, h) do { _Pragma("unroll") for (int m = 0; m < 4; ++m) _Pragma("unroll") for (int k = 0; k < 2; ++k) dst[m][k] = *(const LAS bf16x8*)(lds + PG8_SA(b, h) + aoff + m * 2048 + k * 1024); } while (0)
; #define PG8_LDB(dst, b, h) do { _Pragma("unroll") for (int n = 0; n < 2; ++n) _Pragma("unroll") for (int k = 0; k < 2; ++k) dst[n][k] = *(const LAS bf16x8*)(lds + PG8_SB(b, h) + boff + n * 2048 + k * 1024); } while (0)
; #define PG8_MMA(ai, bj, At, Bt) do { __builtin_amdgcn_s_setprio(1); _Pragma("unroll") for (int m = 0; m < 4; ++m) _Pragma("unroll") for (int n = 0; n < 2; ++n) _Pragma("unroll") for (int k = 0; k < 2; ++k) \
;         acc[ai][bj][m][n] = __builtin_amdgcn_mfma_f32_16x16x32_bf16(Bt[n][k], At[m][k], acc[ai][bj][m][n], 0, 0, 0); __builtin_amdgcn_s_setprio(0); } while (0)
; #define PG8_WAIT_V(n) asm volatile("s_waitcnt vmcnt(" #n ")" ::: "memory")
; #define PG8_WAIT_L(n) asm volatile("s_waitcnt lgkmcnt(" #n ")" ::: "memory")
; template <class Epi>
; __device__ __forceinline__ void gemm_phase(LAS unsigned char* lds, const Gemm g, const Sched& S, const Epi& E) {
;     ...
;         for (int t = 0; t < nt; t += 2) {
;             const bool last = (t == nt - 2);
;             const char* a1 = cA + (size_t)(t + 1) * kstep;
;             const char* a2 = last ? nA : cA + (size_t)(t + 2) * kstep; const char* b2 = last ? nB : cB + (size_t)(t + 2) * kstep;
;             const char* a3 = a2 + kstep; const char* b3 = b2 + kstep;
;             PG8_LDB(B0, 0, 0); PG8_SCHED; PG8_LDA(At, 0, 0); PG8_STAGE(PG8_SA(1, 1), a1 + hstepA, voffA);
;             PG8_WAIT_L(8); PG8_BAR; PG8_WAIT_L(0); PG8_MMA(0, 0, At, B0); PG8_BAR; PG8_SCHED;
;             PG8_LDB(B1, 0, 1); PG8_STAGE(PG8_SB(0, 0), b2, voffB);
;             PG8_BAR; PG8_WAIT_L(0); PG8_MMA(0, 1, At, B1); PG8_BAR;
;             PG8_LDA(At, 0, 1); PG8_STAGE(PG8_SA(0, 0), a2, voffA);
;             PG8_BAR; PG8_WAIT_L(0); PG8_MMA(1, 0, At, B0); PG8_BAR; PG8_SCHED;
;             PG8_STAGE(PG8_SB(0, 1), b2 + hstepB, voffB);
;             PG8_WAIT_V(6); PG8_BAR; PG8_MMA(1, 1, At, B1); PG8_BAR;
.Lresync_y_555:
.LBB0_555:
	s_add_i32 s14, s6, 2
	s_add_u32 s8, s4, 0x80
	s_addc_u32 s7, s5, 0
	s_cmp_eq_u32 s43, s6
	s_cselect_b32 s6, s57, s8
	s_cselect_b32 s7, s55, s7
	s_cselect_b32 s91, s59, s35
	s_cselect_b32 s90, s95, s34
	v_lshl_add_u64 v[192:193], s[4:5], 0, v[136:137]
	s_add_i32 m0, s33, 0xc000
	s_nop 0
	global_load_lds_dwordx4 v[192:193], off
	v_lshl_add_u64 v[192:193], s[4:5], 0, v[138:139]
	s_add_i32 m0, s33, 0xe000
	s_nop 0
	global_load_lds_dwordx4 v[192:193], off
	s_add_i32 s9, 0, 0x10000
	v_add_u32_e32 v160, s9, v156
	ds_read_b128 v[142:145], v160
	ds_read_b128 v[146:149], v160 offset:1024
	ds_read_b128 v[150:153], v160 offset:2048
	ds_read_b128 v[160:163], v160 offset:3072
	ds_read_b128 v[164:167], v159
	ds_read_b128 v[168:171], v159 offset:1024
	ds_read_b128 v[172:175], v159 offset:2048
	ds_read_b128 v[176:179], v159 offset:3072
	ds_read_b128 v[180:183], v159 offset:4096
	ds_read_b128 v[184:187], v159 offset:5120
	ds_read_b128 v[188:191], v159 offset:6144
	ds_read_b128 v[196:199], v159 offset:7168
	s_add_i32 s8, 0, 0x14000
	v_add_u32_e32 v192, s8, v156
	ds_read_b128 v[200:203], v192
	ds_read_b128 v[204:207], v192 offset:1024
	ds_read_b128 v[208:211], v192 offset:2048
	ds_read_b128 v[212:215], v192 offset:3072
	s_waitcnt vmcnt(8)
	s_waitcnt lgkmcnt(0)
	v_mfma_f32_16x16x32_bf16 v[126:129], v[142:145], v[164:167], v[126:129]
	v_mfma_f32_16x16x32_bf16 v[122:125], v[150:153], v[164:167], v[122:125]
	v_mfma_f32_16x16x32_bf16 v[110:113], v[142:145], v[172:175], v[110:113]
	v_mfma_f32_16x16x32_bf16 v[106:109], v[150:153], v[172:175], v[106:109]
	s_barrier
	s_setprio 1
	v_mfma_f32_16x16x32_bf16 v[94:97], v[142:145], v[180:183], v[94:97]
	v_mfma_f32_16x16x32_bf16 v[90:93], v[150:153], v[180:183], v[90:93]
	v_mfma_f32_16x16x32_bf16 v[78:81], v[142:145], v[188:191], v[78:81]
	v_mfma_f32_16x16x32_bf16 v[74:77], v[150:153], v[188:191], v[74:77]
	v_mfma_f32_16x16x32_bf16 v[126:129], v[146:149], v[168:171], v[126:129]
	v_mfma_f32_16x16x32_bf16 v[122:125], v[160:163], v[168:171], v[122:125]
	v_mfma_f32_16x16x32_bf16 v[110:113], v[146:149], v[176:179], v[110:113]
	v_mfma_f32_16x16x32_bf16 v[106:109], v[160:163], v[176:179], v[106:109]
	v_mfma_f32_16x16x32_bf16 v[94:97], v[146:149], v[184:187], v[94:97]
	v_mfma_f32_16x16x32_bf16 v[90:93], v[160:163], v[184:187], v[90:93]
	v_mfma_f32_16x16x32_bf16 v[78:81], v[146:149], v[196:199], v[78:81]
	v_mfma_f32_16x16x32_bf16 v[74:77], v[160:163], v[196:199], v[74:77]
	v_mfma_f32_16x16x32_bf16 v[118:121], v[200:203], v[164:167], v[118:121]
	v_mfma_f32_16x16x32_bf16 v[114:117], v[208:211], v[164:167], v[114:117]
	v_mfma_f32_16x16x32_bf16 v[102:105], v[200:203], v[172:175], v[102:105]
	v_mfma_f32_16x16x32_bf16 v[98:101], v[208:211], v[172:175], v[98:101]
	v_mfma_f32_16x16x32_bf16 v[86:89], v[200:203], v[180:183], v[86:89]
	v_mfma_f32_16x16x32_bf16 v[82:85], v[208:211], v[180:183], v[82:85]
	v_mfma_f32_16x16x32_bf16 v[70:73], v[200:203], v[188:191], v[70:73]
	v_mfma_f32_16x16x32_bf16 v[66:69], v[208:211], v[188:191], v[66:69]
	v_mfma_f32_16x16x32_bf16 v[118:121], v[204:207], v[168:171], v[118:121]
	v_mfma_f32_16x16x32_bf16 v[114:117], v[212:215], v[168:171], v[114:117]
	v_mfma_f32_16x16x32_bf16 v[102:105], v[204:207], v[176:179], v[102:105]
	v_mfma_f32_16x16x32_bf16 v[98:101], v[212:215], v[176:179], v[98:101]
	v_mfma_f32_16x16x32_bf16 v[86:89], v[204:207], v[184:187], v[86:89]
	v_mfma_f32_16x16x32_bf16 v[82:85], v[212:215], v[184:187], v[82:85]
	v_mfma_f32_16x16x32_bf16 v[70:73], v[204:207], v[196:199], v[70:73]
	v_mfma_f32_16x16x32_bf16 v[66:69], v[212:215], v[196:199], v[66:69]
	s_setprio 0
	s_barrier
	s_add_i32 s9, s9, s3
	v_lshl_add_u64 v[192:193], s[90:91], 0, v[0:1]
	s_mov_b32 m0, s9
	v_lshl_add_u64 v[194:195], s[90:91], 0, v[134:135]
	global_load_lds_dwordx4 v[192:193], off
	s_add_i32 m0, s9, 0x2000
	s_nop 0
	global_load_lds_dwordx4 v[194:195], off
	s_mov_b32 m0, s33
	v_lshl_add_u64 v[216:217], s[6:7], 0, v[130:131]
	global_load_lds_dwordx4 v[216:217], off
	v_lshl_add_u64 v[222:223], s[6:7], 0, v[132:133]
	s_mov_b32 m0, s38
	s_nop 0
	global_load_lds_dwordx4 v[222:223], off
	s_add_u32 s90, s90, s76
	s_addc_u32 s91, s91, s77
	s_add_i32 s8, s8, s3
	v_lshl_add_u64 v[224:225], s[90:91], 0, v[0:1]
	s_mov_b32 m0, s8
	v_lshl_add_u64 v[226:227], s[90:91], 0, v[134:135]
	global_load_lds_dwordx4 v[224:225], off
	s_add_i32 m0, s8, 0x2000
	s_nop 0
	global_load_lds_dwordx4 v[226:227], off
	ds_read_b128 v[164:167], v159 offset:16384
	ds_read_b128 v[168:171], v159 offset:17408
	ds_read_b128 v[172:175], v159 offset:18432
	ds_read_b128 v[176:179], v159 offset:19456
	ds_read_b128 v[180:183], v159 offset:20480
	ds_read_b128 v[184:187], v159 offset:21504
	ds_read_b128 v[188:191], v159 offset:22528
	ds_read_b128 v[196:199], v159 offset:23552
	s_waitcnt vmcnt(8)
	s_waitcnt lgkmcnt(0)
	v_mfma_f32_16x16x32_bf16 v[62:65], v[142:145], v[164:167], v[62:65]
	v_mfma_f32_16x16x32_bf16 v[58:61], v[150:153], v[164:167], v[58:61]
	v_mfma_f32_16x16x32_bf16 v[46:49], v[142:145], v[172:175], v[46:49]
	v_mfma_f32_16x16x32_bf16 v[42:45], v[150:153], v[172:175], v[42:45]
	s_barrier
; #define PG8_STAGE(bufoff, gbase, voff) do { _Pragma("unroll") for (int _i = 0; _i < 2; ++_i) \
;         __builtin_amdgcn_global_load_lds((const unsigned*)((const char*)(gbase) + (voff)[_i]), (LAS unsigned*)(lds + (bufoff) + ldsw + _i * 8192), 16, 0, 0); } while (0)
; #define PG8_LDA(dst, b, h) do { _Pragma("unroll") for (int m = 0; m < 4; ++m) _Pragma("unroll") for (int k = 0; k < 2; ++k) dst[m][k] = *(const LAS bf16x8*)(lds + PG8_SA(b, h) + aoff + m * 2048 + k * 1024); } while (0)
; #define PG8_LDB(dst, b, h) do { _Pragma("unroll") for (int n = 0; n < 2; ++n) _Pragma("unroll") for (int k = 0; k < 2; ++k) dst[n][k] = *(const LAS bf16x8*)(lds + PG8_SB(b, h) + boff + n * 2048 + k * 1024); } while (0)
; #define PG8_MMA(ai, bj, At, Bt) do { __builtin_amdgcn_s_setprio(1); _Pragma("unroll") for (int m = 0; m < 4; ++m) _Pragma("unroll") for (int n = 0; n < 2; ++n) _Pragma("unroll") for (int k = 0; k < 2; ++k) \
;         acc[ai][bj][m][n] = __builtin_amdgcn_mfma_f32_16x16x32_bf16(Bt[n][k], At[m][k], acc[ai][bj][m][n], 0, 0, 0); __builtin_amdgcn_s_setprio(0); } while (0)
; #define PG8_WAIT_V(n) asm volatile("s_waitcnt vmcnt(" #n ")" ::: "memory")
; #define PG8_WAIT_L(n) asm volatile("s_waitcnt lgkmcnt(" #n ")" ::: "memory")
; #define PG8_BAR __builtin_amdgcn_s_barrier()
; #define PG8_SCHED __builtin_amdgcn_sched_barrier(0)
; template <class Epi>
; __device__ __forceinline__ void gemm_phase(LAS unsigned char* lds, const Gemm g, const Sched& S, const Epi& E) {
;     ...
;             PG8_BAR; PG8_WAIT_L(0); PG8_MMA(1, 0, At, B0); PG8_BAR; PG8_SCHED;
;             PG8_STAGE(PG8_SB(0, 1), b2 + hstepB, voffB);
;             PG8_WAIT_V(6); PG8_BAR; PG8_MMA(1, 1, At, B1); PG8_BAR;
;             PG8_LDB(B0, 1, 0); PG8_SCHED; PG8_LDA(At, 1, 0); PG8_STAGE(PG8_SA(0, 1), a2 + hstepA, voffA);
;             PG8_WAIT_L(8); PG8_BAR; PG8_WAIT_L(0); PG8_MMA(0, 0, At, B0); PG8_BAR; PG8_SCHED;
;             PG8_LDB(B1, 1, 1); PG8_STAGE(PG8_SB(1, 0), b3, voffB);
;             PG8_BAR; PG8_WAIT_L(0); PG8_MMA(0, 1, At, B1); PG8_BAR;
	s_setprio 1
	v_mfma_f32_16x16x32_bf16 v[30:33], v[142:145], v[180:183], v[30:33]
	v_mfma_f32_16x16x32_bf16 v[26:29], v[150:153], v[180:183], v[26:29]
	v_mfma_f32_16x16x32_bf16 v[14:17], v[142:145], v[188:191], v[14:17]
	v_mfma_f32_16x16x32_bf16 v[10:13], v[150:153], v[188:191], v[10:13]
	v_mfma_f32_16x16x32_bf16 v[62:65], v[146:149], v[168:171], v[62:65]
	v_mfma_f32_16x16x32_bf16 v[58:61], v[160:163], v[168:171], v[58:61]
	v_mfma_f32_16x16x32_bf16 v[46:49], v[146:149], v[176:179], v[46:49]
	v_mfma_f32_16x16x32_bf16 v[42:45], v[160:163], v[176:179], v[42:45]
	v_mfma_f32_16x16x32_bf16 v[30:33], v[146:149], v[184:187], v[30:33]
	v_mfma_f32_16x16x32_bf16 v[26:29], v[160:163], v[184:187], v[26:29]
	v_mfma_f32_16x16x32_bf16 v[14:17], v[146:149], v[196:199], v[14:17]
	v_mfma_f32_16x16x32_bf16 v[10:13], v[160:163], v[196:199], v[10:13]
	v_mfma_f32_16x16x32_bf16 v[54:57], v[200:203], v[164:167], v[54:57]
	v_mfma_f32_16x16x32_bf16 v[50:53], v[208:211], v[164:167], v[50:53]
	v_mfma_f32_16x16x32_bf16 v[38:41], v[200:203], v[172:175], v[38:41]
	v_mfma_f32_16x16x32_bf16 v[34:37], v[208:211], v[172:175], v[34:37]
	v_mfma_f32_16x16x32_bf16 v[22:25], v[200:203], v[180:183], v[22:25]
	v_mfma_f32_16x16x32_bf16 v[18:21], v[208:211], v[180:183], v[18:21]
	v_mfma_f32_16x16x32_bf16 v[6:9], v[200:203], v[188:191], v[6:9]
	v_mfma_f32_16x16x32_bf16 v[2:5], v[208:211], v[188:191], v[2:5]
	v_mfma_f32_16x16x32_bf16 v[54:57], v[204:207], v[168:171], v[54:57]
	v_mfma_f32_16x16x32_bf16 v[50:53], v[212:215], v[168:171], v[50:53]
	v_mfma_f32_16x16x32_bf16 v[38:41], v[204:207], v[176:179], v[38:41]
	v_mfma_f32_16x16x32_bf16 v[34:37], v[212:215], v[176:179], v[34:37]
	v_mfma_f32_16x16x32_bf16 v[22:25], v[204:207], v[184:187], v[22:25]
	v_mfma_f32_16x16x32_bf16 v[18:21], v[212:215], v[184:187], v[18:21]
	v_mfma_f32_16x16x32_bf16 v[6:9], v[204:207], v[196:199], v[6:9]
	v_mfma_f32_16x16x32_bf16 v[2:5], v[212:215], v[196:199], v[2:5]
	s_setprio 0
	s_barrier
	s_add_u32 s6, s6, s36
	s_addc_u32 s7, s7, s37
	s_mov_b32 m0, s39
	v_lshl_add_u64 v[200:201], s[6:7], 0, v[130:131]
	global_load_lds_dwordx4 v[200:201], off
	v_lshl_add_u64 v[200:201], s[6:7], 0, v[132:133]
	s_mov_b32 m0, s40
	s_nop 0
	global_load_lds_dwordx4 v[200:201], off
	s_add_i32 s8, 0, 0x18000
	v_add_u32_e32 v160, s8, v156
	ds_read_b128 v[142:145], v160
	ds_read_b128 v[146:149], v160 offset:1024
	ds_read_b128 v[150:153], v160 offset:2048
	ds_read_b128 v[160:163], v160 offset:3072
	ds_read_b128 v[164:167], v159 offset:32768
	ds_read_b128 v[168:171], v159 offset:33792
	ds_read_b128 v[172:175], v159 offset:34816
	ds_read_b128 v[176:179], v159 offset:35840
	ds_read_b128 v[180:183], v159 offset:36864
	ds_read_b128 v[184:187], v159 offset:37888
	ds_read_b128 v[188:191], v159 offset:38912
	ds_read_b128 v[196:199], v159 offset:39936
	s_add_i32 s6, 0, 0x1c000
	v_add_u32_e32 v212, s6, v156
	ds_read_b128 v[200:203], v212
	ds_read_b128 v[204:207], v212 offset:1024
	ds_read_b128 v[208:211], v212 offset:2048
	ds_read_b128 v[212:215], v212 offset:3072
	s_waitcnt vmcnt(8)
	s_waitcnt lgkmcnt(0)
	v_mfma_f32_16x16x32_bf16 v[126:129], v[142:145], v[164:167], v[126:129]
	v_mfma_f32_16x16x32_bf16 v[122:125], v[150:153], v[164:167], v[122:125]
	v_mfma_f32_16x16x32_bf16 v[110:113], v[142:145], v[172:175], v[110:113]
	v_mfma_f32_16x16x32_bf16 v[106:109], v[150:153], v[172:175], v[106:109]
	s_barrier
	s_setprio 1
	v_mfma_f32_16x16x32_bf16 v[94:97], v[142:145], v[180:183], v[94:97]
	v_mfma_f32_16x16x32_bf16 v[90:93], v[150:153], v[180:183], v[90:93]
	v_mfma_f32_16x16x32_bf16 v[78:81], v[142:145], v[188:191], v[78:81]
	v_mfma_f32_16x16x32_bf16 v[74:77], v[150:153], v[188:191], v[74:77]
	v_mfma_f32_16x16x32_bf16 v[126:129], v[146:149], v[168:171], v[126:129]
	v_mfma_f32_16x16x32_bf16 v[122:125], v[160:163], v[168:171], v[122:125]
	v_mfma_f32_16x16x32_bf16 v[110:113], v[146:149], v[176:179], v[110:113]
	v_mfma_f32_16x16x32_bf16 v[106:109], v[160:163], v[176:179], v[106:109]
	v_mfma_f32_16x16x32_bf16 v[94:97], v[146:149], v[184:187], v[94:97]
	v_mfma_f32_16x16x32_bf16 v[90:93], v[160:163], v[184:187], v[90:93]
	v_mfma_f32_16x16x32_bf16 v[78:81], v[146:149], v[196:199], v[78:81]
	v_mfma_f32_16x16x32_bf16 v[74:77], v[160:163], v[196:199], v[74:77]
	v_mfma_f32_16x16x32_bf16 v[118:121], v[200:203], v[164:167], v[118:121]
	v_mfma_f32_16x16x32_bf16 v[114:117], v[208:211], v[164:167], v[114:117]
	v_mfma_f32_16x16x32_bf16 v[102:105], v[200:203], v[172:175], v[102:105]
	v_mfma_f32_16x16x32_bf16 v[98:101], v[208:211], v[172:175], v[98:101]
	v_mfma_f32_16x16x32_bf16 v[86:89], v[200:203], v[180:183], v[86:89]
	v_mfma_f32_16x16x32_bf16 v[82:85], v[208:211], v[180:183], v[82:85]
	v_mfma_f32_16x16x32_bf16 v[70:73], v[200:203], v[188:191], v[70:73]
	v_mfma_f32_16x16x32_bf16 v[66:69], v[208:211], v[188:191], v[66:69]
	v_mfma_f32_16x16x32_bf16 v[118:121], v[204:207], v[168:171], v[118:121]
	v_mfma_f32_16x16x32_bf16 v[114:117], v[212:215], v[168:171], v[114:117]
	v_mfma_f32_16x16x32_bf16 v[102:105], v[204:207], v[176:179], v[102:105]
	v_mfma_f32_16x16x32_bf16 v[98:101], v[212:215], v[176:179], v[98:101]
	v_mfma_f32_16x16x32_bf16 v[86:89], v[204:207], v[184:187], v[86:89]
	v_mfma_f32_16x16x32_bf16 v[82:85], v[212:215], v[184:187], v[82:85]
	v_mfma_f32_16x16x32_bf16 v[70:73], v[204:207], v[196:199], v[70:73]
	v_mfma_f32_16x16x32_bf16 v[66:69], v[212:215], v[196:199], v[66:69]
	s_setprio 0
	s_barrier
; #define PG8_STAGE(bufoff, gbase, voff) do { _Pragma("unroll") for (int _i = 0; _i < 2; ++_i) \
;         __builtin_amdgcn_global_load_lds((const unsigned*)((const char*)(gbase) + (voff)[_i]), (LAS unsigned*)(lds + (bufoff) + ldsw + _i * 8192), 16, 0, 0); } while (0)
; #define PG8_LDA(dst, b, h) do { _Pragma("unroll") for (int m = 0; m < 4; ++m) _Pragma("unroll") for (int k = 0; k < 2; ++k) dst[m][k] = *(const LAS bf16x8*)(lds + PG8_SA(b, h) + aoff + m * 2048 + k * 1024); } while (0)
; #define PG8_MMA(ai, bj, At, Bt) do { __builtin_amdgcn_s_setprio(1); _Pragma("unroll") for (int m = 0; m < 4; ++m) _Pragma("unroll") for (int n = 0; n < 2; ++n) _Pragma("unroll") for (int k = 0; k < 2; ++k) \
;         acc[ai][bj][m][n] = __builtin_amdgcn_mfma_f32_16x16x32_bf16(Bt[n][k], At[m][k], acc[ai][bj][m][n], 0, 0, 0); __builtin_amdgcn_s_setprio(0); } while (0)
; #define PG8_WAIT_V(n) asm volatile("s_waitcnt vmcnt(" #n ")" ::: "memory")
; #define PG8_WAIT_L(n) asm volatile("s_waitcnt lgkmcnt(" #n ")" ::: "memory")
; #define PG8_BAR __builtin_amdgcn_s_barrier()
; #define PG8_SCHED __builtin_amdgcn_sched_barrier(0)
; template <class Epi>
; __device__ __forceinline__ void gemm_phase(LAS unsigned char* lds, const Gemm g, const Sched& S, const Epi& E) {
;     ...
;             PG8_LDA(At, 1, 1); PG8_STAGE(PG8_SA(1, 0), a3, voffA);
;             PG8_BAR; PG8_WAIT_L(0); PG8_MMA(1, 0, At, B0); PG8_BAR; PG8_SCHED;
;             PG8_STAGE(PG8_SB(1, 1), b3 + hstepB, voffB);
;             PG8_WAIT_V(6); PG8_BAR; PG8_MMA(1, 1, At, B1); PG8_BAR;
;         }
	s_add_i32 s7, s8, s3
	v_lshl_add_u64 v[192:193], v[192:193], 0, s[60:61]
	s_mov_b32 m0, s7
	s_nop 0
	global_load_lds_dwordx4 v[192:193], off
	v_lshl_add_u64 v[192:193], v[194:195], 0, s[60:61]
	s_add_i32 m0, s7, 0x2000
	s_nop 0
	global_load_lds_dwordx4 v[192:193], off
	s_mov_b32 m0, s41
	v_lshl_add_u64 v[192:193], v[216:217], 0, s[60:61]
	global_load_lds_dwordx4 v[192:193], off
	v_lshl_add_u64 v[192:193], v[222:223], 0, s[60:61]
	s_mov_b32 m0, s42
	s_nop 0
	global_load_lds_dwordx4 v[192:193], off
	s_add_i32 s6, s6, s3
	v_lshl_add_u64 v[192:193], v[224:225], 0, s[60:61]
	s_mov_b32 m0, s6
	s_nop 0
	global_load_lds_dwordx4 v[192:193], off
	v_lshl_add_u64 v[192:193], v[226:227], 0, s[60:61]
	s_add_i32 m0, s6, 0x2000
	s_nop 0
	global_load_lds_dwordx4 v[192:193], off
	ds_read_b128 v[164:167], v159 offset:49152
	ds_read_b128 v[168:171], v159 offset:50176
	ds_read_b128 v[172:175], v159 offset:51200
	ds_read_b128 v[176:179], v159 offset:52224
	ds_read_b128 v[180:183], v159 offset:53248
	ds_read_b128 v[184:187], v159 offset:54272
	ds_read_b128 v[188:191], v159 offset:55296
	ds_read_b128 v[196:199], v159 offset:56320
	s_waitcnt vmcnt(8)
	s_waitcnt lgkmcnt(0)
	v_mfma_f32_16x16x32_bf16 v[62:65], v[142:145], v[164:167], v[62:65]
	v_mfma_f32_16x16x32_bf16 v[58:61], v[150:153], v[164:167], v[58:61]
	v_mfma_f32_16x16x32_bf16 v[46:49], v[142:145], v[172:175], v[46:49]
	v_mfma_f32_16x16x32_bf16 v[42:45], v[150:153], v[172:175], v[42:45]
	s_barrier
	s_setprio 1
	v_mfma_f32_16x16x32_bf16 v[30:33], v[142:145], v[180:183], v[30:33]
	v_mfma_f32_16x16x32_bf16 v[26:29], v[150:153], v[180:183], v[26:29]
	v_mfma_f32_16x16x32_bf16 v[14:17], v[142:145], v[188:191], v[14:17]
	v_mfma_f32_16x16x32_bf16 v[10:13], v[150:153], v[188:191], v[10:13]
	v_mfma_f32_16x16x32_bf16 v[62:65], v[146:149], v[168:171], v[62:65]
	v_mfma_f32_16x16x32_bf16 v[58:61], v[160:163], v[168:171], v[58:61]
	v_mfma_f32_16x16x32_bf16 v[46:49], v[146:149], v[176:179], v[46:49]
	v_mfma_f32_16x16x32_bf16 v[42:45], v[160:163], v[176:179], v[42:45]
	v_mfma_f32_16x16x32_bf16 v[30:33], v[146:149], v[184:187], v[30:33]
	v_mfma_f32_16x16x32_bf16 v[26:29], v[160:163], v[184:187], v[26:29]
	v_mfma_f32_16x16x32_bf16 v[14:17], v[146:149], v[196:199], v[14:17]
	v_mfma_f32_16x16x32_bf16 v[10:13], v[160:163], v[196:199], v[10:13]
	v_mfma_f32_16x16x32_bf16 v[54:57], v[200:203], v[164:167], v[54:57]
	v_mfma_f32_16x16x32_bf16 v[50:53], v[208:211], v[164:167], v[50:53]
	v_mfma_f32_16x16x32_bf16 v[38:41], v[200:203], v[172:175], v[38:41]
	v_mfma_f32_16x16x32_bf16 v[34:37], v[208:211], v[172:175], v[34:37]
	v_mfma_f32_16x16x32_bf16 v[22:25], v[200:203], v[180:183], v[22:25]
	v_mfma_f32_16x16x32_bf16 v[18:21], v[208:211], v[180:183], v[18:21]
	v_mfma_f32_16x16x32_bf16 v[6:9], v[200:203], v[188:191], v[6:9]
	v_mfma_f32_16x16x32_bf16 v[2:5], v[208:211], v[188:191], v[2:5]
	v_mfma_f32_16x16x32_bf16 v[54:57], v[204:207], v[168:171], v[54:57]
	v_mfma_f32_16x16x32_bf16 v[50:53], v[212:215], v[168:171], v[50:53]
	v_mfma_f32_16x16x32_bf16 v[38:41], v[204:207], v[176:179], v[38:41]
	v_mfma_f32_16x16x32_bf16 v[34:37], v[212:215], v[176:179], v[34:37]
	v_mfma_f32_16x16x32_bf16 v[22:25], v[204:207], v[184:187], v[22:25]
	v_mfma_f32_16x16x32_bf16 v[18:21], v[212:215], v[184:187], v[18:21]
	v_mfma_f32_16x16x32_bf16 v[6:9], v[204:207], v[196:199], v[6:9]
	v_mfma_f32_16x16x32_bf16 v[2:5], v[212:215], v[196:199], v[2:5]
	s_setprio 0
	s_add_u32 s4, s4, 0x100
	s_addc_u32 s5, s5, 0
	s_add_u32 s34, s34, 0x100
	s_addc_u32 s35, s35, 0
	s_cmp_ge_u32 s14, s73
	s_mov_b32 s6, s14
	s_barrier
	s_cbranch_scc0 .LBB0_555
	v_readfirstlane_b32 s98, v219
	s_nop 1
	s_bitcmp1_b32 s98, 8
	s_cbranch_scc1 .Lresync_x_555
	s_barrier

; #define PG8_STAGE(bufoff, gbase, voff) do { _Pragma("unroll") for (int _i = 0; _i < 2; ++_i) \
;         __builtin_amdgcn_global_load_lds((const unsigned*)((const char*)(gbase) + (voff)[_i]), (LAS unsigned*)(lds + (bufoff) + ldsw + _i * 8192), 16, 0, 0); } while (0)
; #define PG8_LDA(dst, b, h) do { _Pragma("unroll") for (int m = 0; m < 4; ++m) _Pragma("unroll") for (int k = 0; k < 2; ++k) dst[m][k] = *(const LAS bf16x8*)(lds + PG8_SA(b, h) + aoff + m * 2048 + k * 1024); } while (0)
; #define PG8_LDB(dst, b, h) do { _Pragma("unroll") for (int n = 0; n < 2; ++n) _Pragma("unroll") for (int k = 0; k < 2; ++k) dst[n][k] = *(const LAS bf16x8*)(lds + PG8_SB(b, h) + boff + n * 2048 + k * 1024); } while (0)
; #define PG8_MMA(ai, bj, At, Bt) do { __builtin_amdgcn_s_setprio(1); _Pragma("unroll") for (int m = 0; m < 4; ++m) _Pragma("unroll") for (int n = 0; n < 2; ++n) _Pragma("unroll") for (int k = 0; k < 2; ++k) \
;         acc[ai][bj][m][n] = __builtin_amdgcn_mfma_f32_16x16x32_bf16(Bt[n][k], At[m][k], acc[ai][bj][m][n], 0, 0, 0); __builtin_amdgcn_s_setprio(0); } while (0)
; #define PG8_WAIT_V(n) asm volatile("s_waitcnt vmcnt(" #n ")" ::: "memory")
; #define PG8_WAIT_L(n) asm volatile("s_waitcnt lgkmcnt(" #n ")" ::: "memory")
; template <class Epi>
; __device__ __forceinline__ void gemm_phase(LAS unsigned char* lds, const Gemm g, const Sched& S, const Epi& E) {
;     ...
;         for (int t = 0; t < nt; t += 2) {
;             const bool last = (t == nt - 2);
;             const char* a1 = cA + (size_t)(t + 1) * kstep;
;             const char* a2 = last ? nA : cA + (size_t)(t + 2) * kstep; const char* b2 = last ? nB : cB + (size_t)(t + 2) * kstep;
;             const char* a3 = a2 + kstep; const char* b3 = b2 + kstep;
;             PG8_LDB(B0, 0, 0); PG8_SCHED; PG8_LDA(At, 0, 0); PG8_STAGE(PG8_SA(1, 1), a1 + hstepA, voffA);
;             PG8_WAIT_L(8); PG8_BAR; PG8_WAIT_L(0); PG8_MMA(0, 0, At, B0); PG8_BAR; PG8_SCHED;
;             PG8_LDB(B1, 0, 1); PG8_STAGE(PG8_SB(0, 0), b2, voffB);
;             PG8_BAR; PG8_WAIT_L(0); PG8_MMA(0, 1, At, B1); PG8_BAR;
;             PG8_LDA(At, 0, 1); PG8_STAGE(PG8_SA(0, 0), a2, voffA);
;             PG8_BAR; PG8_WAIT_L(0); PG8_MMA(1, 0, At, B0); PG8_BAR; PG8_SCHED;
;             PG8_STAGE(PG8_SB(0, 1), b2 + hstepB, voffB);
;             PG8_WAIT_V(6); PG8_BAR; PG8_MMA(1, 1, At, B1); PG8_BAR;
.Lresync_y_649:
.LBB0_649:
	s_add_i32 s14, s4, 2
	s_add_u32 s8, s0, 0x80
	s_addc_u32 s5, s1, 0
	s_cmp_eq_u32 s95, s4
	s_cselect_b32 s4, s48, s8
	s_cselect_b32 s5, s33, s5
	s_cselect_b32 s87, s51, s35
	s_cselect_b32 s86, s55, s34
	v_lshl_add_u64 v[176:177], s[0:1], 0, v[188:189]
	s_add_i32 m0, s89, 0xc000
	s_nop 0
	global_load_lds_dwordx4 v[176:177], off
	v_lshl_add_u64 v[176:177], s[0:1], 0, v[190:191]
	s_add_i32 m0, s89, 0xe000
	s_nop 0
	global_load_lds_dwordx4 v[176:177], off
	s_add_i32 s9, 0, 0x10000
	v_add_u32_e32 v144, s9, v236
	ds_read_b128 v[132:135], v144
	ds_read_b128 v[136:139], v144 offset:1024
	ds_read_b128 v[140:143], v144 offset:2048
	ds_read_b128 v[144:147], v144 offset:3072
	ds_read_b128 v[148:151], v239
	ds_read_b128 v[152:155], v239 offset:1024
	ds_read_b128 v[156:159], v239 offset:2048
	ds_read_b128 v[160:163], v239 offset:3072
	ds_read_b128 v[164:167], v239 offset:4096
	ds_read_b128 v[168:171], v239 offset:5120
	ds_read_b128 v[172:175], v239 offset:6144
	ds_read_b128 v[196:199], v239 offset:7168
	s_add_i32 s8, 0, 0x14000
	v_add_u32_e32 v176, s8, v236
	ds_read_b128 v[200:203], v176
	ds_read_b128 v[204:207], v176 offset:1024
	ds_read_b128 v[208:211], v176 offset:2048
	ds_read_b128 v[212:215], v176 offset:3072
	s_waitcnt vmcnt(8)
	s_waitcnt lgkmcnt(0)
	v_mfma_f32_16x16x32_bf16 v[126:129], v[132:135], v[148:151], v[126:129]
	v_mfma_f32_16x16x32_bf16 v[122:125], v[140:143], v[148:151], v[122:125]
	v_mfma_f32_16x16x32_bf16 v[110:113], v[132:135], v[156:159], v[110:113]
	v_mfma_f32_16x16x32_bf16 v[106:109], v[140:143], v[156:159], v[106:109]
	s_barrier
	s_setprio 1
	v_mfma_f32_16x16x32_bf16 v[94:97], v[132:135], v[164:167], v[94:97]
	v_mfma_f32_16x16x32_bf16 v[90:93], v[140:143], v[164:167], v[90:93]
	v_mfma_f32_16x16x32_bf16 v[78:81], v[132:135], v[172:175], v[78:81]
	v_mfma_f32_16x16x32_bf16 v[74:77], v[140:143], v[172:175], v[74:77]
	v_mfma_f32_16x16x32_bf16 v[126:129], v[136:139], v[152:155], v[126:129]
	v_mfma_f32_16x16x32_bf16 v[122:125], v[144:147], v[152:155], v[122:125]
	v_mfma_f32_16x16x32_bf16 v[110:113], v[136:139], v[160:163], v[110:113]
	v_mfma_f32_16x16x32_bf16 v[106:109], v[144:147], v[160:163], v[106:109]
	v_mfma_f32_16x16x32_bf16 v[94:97], v[136:139], v[168:171], v[94:97]
	v_mfma_f32_16x16x32_bf16 v[90:93], v[144:147], v[168:171], v[90:93]
	v_mfma_f32_16x16x32_bf16 v[78:81], v[136:139], v[196:199], v[78:81]
	v_mfma_f32_16x16x32_bf16 v[74:77], v[144:147], v[196:199], v[74:77]
	v_mfma_f32_16x16x32_bf16 v[118:121], v[200:203], v[148:151], v[118:121]
	v_mfma_f32_16x16x32_bf16 v[114:117], v[208:211], v[148:151], v[114:117]
	v_mfma_f32_16x16x32_bf16 v[102:105], v[200:203], v[156:159], v[102:105]
	v_mfma_f32_16x16x32_bf16 v[98:101], v[208:211], v[156:159], v[98:101]
	v_mfma_f32_16x16x32_bf16 v[86:89], v[200:203], v[164:167], v[86:89]
	v_mfma_f32_16x16x32_bf16 v[82:85], v[208:211], v[164:167], v[82:85]
	v_mfma_f32_16x16x32_bf16 v[70:73], v[200:203], v[172:175], v[70:73]
	v_mfma_f32_16x16x32_bf16 v[66:69], v[208:211], v[172:175], v[66:69]
	v_mfma_f32_16x16x32_bf16 v[118:121], v[204:207], v[152:155], v[118:121]
	v_mfma_f32_16x16x32_bf16 v[114:117], v[212:215], v[152:155], v[114:117]
	v_mfma_f32_16x16x32_bf16 v[102:105], v[204:207], v[160:163], v[102:105]
	v_mfma_f32_16x16x32_bf16 v[98:101], v[212:215], v[160:163], v[98:101]
	v_mfma_f32_16x16x32_bf16 v[86:89], v[204:207], v[168:171], v[86:89]
	v_mfma_f32_16x16x32_bf16 v[82:85], v[212:215], v[168:171], v[82:85]
	v_mfma_f32_16x16x32_bf16 v[70:73], v[204:207], v[196:199], v[70:73]
	v_mfma_f32_16x16x32_bf16 v[66:69], v[212:215], v[196:199], v[66:69]
	s_setprio 0
	s_barrier
	s_add_i32 s9, s9, s88
	v_lshl_add_u64 v[176:177], s[86:87], 0, v[180:181]
	s_mov_b32 m0, s9
	v_lshl_add_u64 v[192:193], s[86:87], 0, v[184:185]
	global_load_lds_dwordx4 v[176:177], off
	s_add_i32 m0, s9, 0x2000
	s_nop 0
	global_load_lds_dwordx4 v[192:193], off
	s_mov_b32 m0, s89
	v_lshl_add_u64 v[194:195], s[4:5], 0, v[178:179]
	global_load_lds_dwordx4 v[194:195], off
	v_lshl_add_u64 v[216:217], s[4:5], 0, v[182:183]
	s_mov_b32 m0, s90
	s_nop 0
	global_load_lds_dwordx4 v[216:217], off
	s_add_u32 s56, s86, s36
	s_addc_u32 s57, s87, s37
	s_add_i32 s8, s8, s88
	v_lshl_add_u64 v[222:223], s[56:57], 0, v[180:181]
	s_mov_b32 m0, s8
	v_lshl_add_u64 v[224:225], s[56:57], 0, v[184:185]
	global_load_lds_dwordx4 v[222:223], off
	s_add_i32 m0, s8, 0x2000
	s_nop 0
	global_load_lds_dwordx4 v[224:225], off
	ds_read_b128 v[148:151], v239 offset:16384
	ds_read_b128 v[152:155], v239 offset:17408
	ds_read_b128 v[156:159], v239 offset:18432
	ds_read_b128 v[160:163], v239 offset:19456
	ds_read_b128 v[164:167], v239 offset:20480
	ds_read_b128 v[168:171], v239 offset:21504
	ds_read_b128 v[172:175], v239 offset:22528
	ds_read_b128 v[196:199], v239 offset:23552
	s_waitcnt vmcnt(8)
	s_waitcnt lgkmcnt(0)
	v_mfma_f32_16x16x32_bf16 v[62:65], v[132:135], v[148:151], v[62:65]
	v_mfma_f32_16x16x32_bf16 v[58:61], v[140:143], v[148:151], v[58:61]
	v_mfma_f32_16x16x32_bf16 v[46:49], v[132:135], v[156:159], v[46:49]
	v_mfma_f32_16x16x32_bf16 v[42:45], v[140:143], v[156:159], v[42:45]
	s_barrier
; #define PG8_STAGE(bufoff, gbase, voff) do { _Pragma("unroll") for (int _i = 0; _i < 2; ++_i) \
;         __builtin_amdgcn_global_load_lds((const unsigned*)((const char*)(gbase) + (voff)[_i]), (LAS unsigned*)(lds + (bufoff) + ldsw + _i * 8192), 16, 0, 0); } while (0)
; #define PG8_LDA(dst, b, h) do { _Pragma("unroll") for (int m = 0; m < 4; ++m) _Pragma("unroll") for (int k = 0; k < 2; ++k) dst[m][k] = *(const LAS bf16x8*)(lds + PG8_SA(b, h) + aoff + m * 2048 + k * 1024); } while (0)
; #define PG8_LDB(dst, b, h) do { _Pragma("unroll") for (int n = 0; n < 2; ++n) _Pragma("unroll") for (int k = 0; k < 2; ++k) dst[n][k] = *(const LAS bf16x8*)(lds + PG8_SB(b, h) + boff + n * 2048 + k * 1024); } while (0)
; #define PG8_MMA(ai, bj, At, Bt) do { __builtin_amdgcn_s_setprio(1); _Pragma("unroll") for (int m = 0; m < 4; ++m) _Pragma("unroll") for (int n = 0; n < 2; ++n) _Pragma("unroll") for (int k = 0; k < 2; ++k) \
;         acc[ai][bj][m][n] = __builtin_amdgcn_mfma_f32_16x16x32_bf16(Bt[n][k], At[m][k], acc[ai][bj][m][n], 0, 0, 0); __builtin_amdgcn_s_setprio(0); } while (0)
; #define PG8_WAIT_V(n) asm volatile("s_waitcnt vmcnt(" #n ")" ::: "memory")
; #define PG8_WAIT_L(n) asm volatile("s_waitcnt lgkmcnt(" #n ")" ::: "memory")
; #define PG8_BAR __builtin_amdgcn_s_barrier()
; #define PG8_SCHED __builtin_amdgcn_sched_barrier(0)
; template <class Epi>
; __device__ __forceinline__ void gemm_phase(LAS unsigned char* lds, const Gemm g, const Sched& S, const Epi& E) {
;     ...
;             PG8_BAR; PG8_WAIT_L(0); PG8_MMA(1, 0, At, B0); PG8_BAR; PG8_SCHED;
;             PG8_STAGE(PG8_SB(0, 1), b2 + hstepB, voffB);
;             PG8_WAIT_V(6); PG8_BAR; PG8_MMA(1, 1, At, B1); PG8_BAR;
;             PG8_LDB(B0, 1, 0); PG8_SCHED; PG8_LDA(At, 1, 0); PG8_STAGE(PG8_SA(0, 1), a2 + hstepA, voffA);
;             PG8_WAIT_L(8); PG8_BAR; PG8_WAIT_L(0); PG8_MMA(0, 0, At, B0); PG8_BAR; PG8_SCHED;
;             PG8_LDB(B1, 1, 1); PG8_STAGE(PG8_SB(1, 0), b3, voffB);
;             PG8_BAR; PG8_WAIT_L(0); PG8_MMA(0, 1, At, B1); PG8_BAR;
	s_setprio 1
	v_mfma_f32_16x16x32_bf16 v[30:33], v[132:135], v[164:167], v[30:33]
	v_mfma_f32_16x16x32_bf16 v[26:29], v[140:143], v[164:167], v[26:29]
	v_mfma_f32_16x16x32_bf16 v[14:17], v[132:135], v[172:175], v[14:17]
	v_mfma_f32_16x16x32_bf16 v[10:13], v[140:143], v[172:175], v[10:13]
	v_mfma_f32_16x16x32_bf16 v[62:65], v[136:139], v[152:155], v[62:65]
	v_mfma_f32_16x16x32_bf16 v[58:61], v[144:147], v[152:155], v[58:61]
	v_mfma_f32_16x16x32_bf16 v[46:49], v[136:139], v[160:163], v[46:49]
	v_mfma_f32_16x16x32_bf16 v[42:45], v[144:147], v[160:163], v[42:45]
	v_mfma_f32_16x16x32_bf16 v[30:33], v[136:139], v[168:171], v[30:33]
	v_mfma_f32_16x16x32_bf16 v[26:29], v[144:147], v[168:171], v[26:29]
	v_mfma_f32_16x16x32_bf16 v[14:17], v[136:139], v[196:199], v[14:17]
	v_mfma_f32_16x16x32_bf16 v[10:13], v[144:147], v[196:199], v[10:13]
	v_mfma_f32_16x16x32_bf16 v[54:57], v[200:203], v[148:151], v[54:57]
	v_mfma_f32_16x16x32_bf16 v[50:53], v[208:211], v[148:151], v[50:53]
	v_mfma_f32_16x16x32_bf16 v[38:41], v[200:203], v[156:159], v[38:41]
	v_mfma_f32_16x16x32_bf16 v[34:37], v[208:211], v[156:159], v[34:37]
	v_mfma_f32_16x16x32_bf16 v[22:25], v[200:203], v[164:167], v[22:25]
	v_mfma_f32_16x16x32_bf16 v[18:21], v[208:211], v[164:167], v[18:21]
	v_mfma_f32_16x16x32_bf16 v[6:9], v[200:203], v[172:175], v[6:9]
	v_mfma_f32_16x16x32_bf16 v[2:5], v[208:211], v[172:175], v[2:5]
	v_mfma_f32_16x16x32_bf16 v[54:57], v[204:207], v[152:155], v[54:57]
	v_mfma_f32_16x16x32_bf16 v[50:53], v[212:215], v[152:155], v[50:53]
	v_mfma_f32_16x16x32_bf16 v[38:41], v[204:207], v[160:163], v[38:41]
	v_mfma_f32_16x16x32_bf16 v[34:37], v[212:215], v[160:163], v[34:37]
	v_mfma_f32_16x16x32_bf16 v[22:25], v[204:207], v[168:171], v[22:25]
	v_mfma_f32_16x16x32_bf16 v[18:21], v[212:215], v[168:171], v[18:21]
	v_mfma_f32_16x16x32_bf16 v[6:9], v[204:207], v[196:199], v[6:9]
	v_mfma_f32_16x16x32_bf16 v[2:5], v[212:215], v[196:199], v[2:5]
	s_setprio 0
	s_barrier
	s_add_u32 s4, s4, s6
	s_addc_u32 s5, s5, s7
	s_mov_b32 m0, s91
	v_lshl_add_u64 v[200:201], s[4:5], 0, v[178:179]
	global_load_lds_dwordx4 v[200:201], off
	v_lshl_add_u64 v[200:201], s[4:5], 0, v[182:183]
	s_mov_b32 m0, s92
	s_nop 0
	global_load_lds_dwordx4 v[200:201], off
	s_add_i32 s8, 0, 0x18000
	v_add_u32_e32 v144, s8, v236
	ds_read_b128 v[132:135], v144
	ds_read_b128 v[136:139], v144 offset:1024
	ds_read_b128 v[140:143], v144 offset:2048
	ds_read_b128 v[144:147], v144 offset:3072
	ds_read_b128 v[148:151], v239 offset:32768
	ds_read_b128 v[152:155], v239 offset:33792
	ds_read_b128 v[156:159], v239 offset:34816
	ds_read_b128 v[160:163], v239 offset:35840
	ds_read_b128 v[164:167], v239 offset:36864
	ds_read_b128 v[168:171], v239 offset:37888
	ds_read_b128 v[172:175], v239 offset:38912
	ds_read_b128 v[196:199], v239 offset:39936
	s_add_i32 s4, 0, 0x1c000
	v_add_u32_e32 v212, s4, v236
	ds_read_b128 v[200:203], v212
	ds_read_b128 v[204:207], v212 offset:1024
	ds_read_b128 v[208:211], v212 offset:2048
	ds_read_b128 v[212:215], v212 offset:3072
	s_waitcnt vmcnt(8)
	s_waitcnt lgkmcnt(0)
	v_mfma_f32_16x16x32_bf16 v[126:129], v[132:135], v[148:151], v[126:129]
	v_mfma_f32_16x16x32_bf16 v[122:125], v[140:143], v[148:151], v[122:125]
	v_mfma_f32_16x16x32_bf16 v[110:113], v[132:135], v[156:159], v[110:113]
	v_mfma_f32_16x16x32_bf16 v[106:109], v[140:143], v[156:159], v[106:109]
	s_barrier
	s_setprio 1
	v_mfma_f32_16x16x32_bf16 v[94:97], v[132:135], v[164:167], v[94:97]
	v_mfma_f32_16x16x32_bf16 v[90:93], v[140:143], v[164:167], v[90:93]
	v_mfma_f32_16x16x32_bf16 v[78:81], v[132:135], v[172:175], v[78:81]
	v_mfma_f32_16x16x32_bf16 v[74:77], v[140:143], v[172:175], v[74:77]
	v_mfma_f32_16x16x32_bf16 v[126:129], v[136:139], v[152:155], v[126:129]
	v_mfma_f32_16x16x32_bf16 v[122:125], v[144:147], v[152:155], v[122:125]
	v_mfma_f32_16x16x32_bf16 v[110:113], v[136:139], v[160:163], v[110:113]
	v_mfma_f32_16x16x32_bf16 v[106:109], v[144:147], v[160:163], v[106:109]
	v_mfma_f32_16x16x32_bf16 v[94:97], v[136:139], v[168:171], v[94:97]
	v_mfma_f32_16x16x32_bf16 v[90:93], v[144:147], v[168:171], v[90:93]
	v_mfma_f32_16x16x32_bf16 v[78:81], v[136:139], v[196:199], v[78:81]
	v_mfma_f32_16x16x32_bf16 v[74:77], v[144:147], v[196:199], v[74:77]
	v_mfma_f32_16x16x32_bf16 v[118:121], v[200:203], v[148:151], v[118:121]
	v_mfma_f32_16x16x32_bf16 v[114:117], v[208:211], v[148:151], v[114:117]
	v_mfma_f32_16x16x32_bf16 v[102:105], v[200:203], v[156:159], v[102:105]
	v_mfma_f32_16x16x32_bf16 v[98:101], v[208:211], v[156:159], v[98:101]
	v_mfma_f32_16x16x32_bf16 v[86:89], v[200:203], v[164:167], v[86:89]
	v_mfma_f32_16x16x32_bf16 v[82:85], v[208:211], v[164:167], v[82:85]
	v_mfma_f32_16x16x32_bf16 v[70:73], v[200:203], v[172:175], v[70:73]
	v_mfma_f32_16x16x32_bf16 v[66:69], v[208:211], v[172:175], v[66:69]
	v_mfma_f32_16x16x32_bf16 v[118:121], v[204:207], v[152:155], v[118:121]
	v_mfma_f32_16x16x32_bf16 v[114:117], v[212:215], v[152:155], v[114:117]
	v_mfma_f32_16x16x32_bf16 v[102:105], v[204:207], v[160:163], v[102:105]
	v_mfma_f32_16x16x32_bf16 v[98:101], v[212:215], v[160:163], v[98:101]
	v_mfma_f32_16x16x32_bf16 v[86:89], v[204:207], v[168:171], v[86:89]
	v_mfma_f32_16x16x32_bf16 v[82:85], v[212:215], v[168:171], v[82:85]
	v_mfma_f32_16x16x32_bf16 v[70:73], v[204:207], v[196:199], v[70:73]
	v_mfma_f32_16x16x32_bf16 v[66:69], v[212:215], v[196:199], v[66:69]
	s_setprio 0
	s_barrier
; #define PG8_STAGE(bufoff, gbase, voff) do { _Pragma("unroll") for (int _i = 0; _i < 2; ++_i) \
;         __builtin_amdgcn_global_load_lds((const unsigned*)((const char*)(gbase) + (voff)[_i]), (LAS unsigned*)(lds + (bufoff) + ldsw + _i * 8192), 16, 0, 0); } while (0)
; #define PG8_LDA(dst, b, h) do { _Pragma("unroll") for (int m = 0; m < 4; ++m) _Pragma("unroll") for (int k = 0; k < 2; ++k) dst[m][k] = *(const LAS bf16x8*)(lds + PG8_SA(b, h) + aoff + m * 2048 + k * 1024); } while (0)
; #define PG8_MMA(ai, bj, At, Bt) do { __builtin_amdgcn_s_setprio(1); _Pragma("unroll") for (int m = 0; m < 4; ++m) _Pragma("unroll") for (int n = 0; n < 2; ++n) _Pragma("unroll") for (int k = 0; k < 2; ++k) \
;         acc[ai][bj][m][n] = __builtin_amdgcn_mfma_f32_16x16x32_bf16(Bt[n][k], At[m][k], acc[ai][bj][m][n], 0, 0, 0); __builtin_amdgcn_s_setprio(0); } while (0)
; #define PG8_WAIT_V(n) asm volatile("s_waitcnt vmcnt(" #n ")" ::: "memory")
; #define PG8_WAIT_L(n) asm volatile("s_waitcnt lgkmcnt(" #n ")" ::: "memory")
; #define PG8_BAR __builtin_amdgcn_s_barrier()
; #define PG8_SCHED __builtin_amdgcn_sched_barrier(0)
; template <class Epi>
; __device__ __forceinline__ void gemm_phase(LAS unsigned char* lds, const Gemm g, const Sched& S, const Epi& E) {
;     ...
;             PG8_LDA(At, 1, 1); PG8_STAGE(PG8_SA(1, 0), a3, voffA);
;             PG8_BAR; PG8_WAIT_L(0); PG8_MMA(1, 0, At, B0); PG8_BAR; PG8_SCHED;
;             PG8_STAGE(PG8_SB(1, 1), b3 + hstepB, voffB);
;             PG8_WAIT_V(6); PG8_BAR; PG8_MMA(1, 1, At, B1); PG8_BAR;
;         }
	s_add_i32 s5, s8, s88
	v_lshl_add_u64 v[176:177], v[176:177], 0, s[60:61]
	s_mov_b32 m0, s5
	s_nop 0
	global_load_lds_dwordx4 v[176:177], off
	v_lshl_add_u64 v[176:177], v[192:193], 0, s[60:61]
	s_add_i32 m0, s5, 0x2000
	s_nop 0
	global_load_lds_dwordx4 v[176:177], off
	s_mov_b32 m0, s93
	v_lshl_add_u64 v[176:177], v[194:195], 0, s[60:61]
	global_load_lds_dwordx4 v[176:177], off
	v_lshl_add_u64 v[176:177], v[216:217], 0, s[60:61]
	s_mov_b32 m0, s94
	s_nop 0
	global_load_lds_dwordx4 v[176:177], off
	s_add_i32 s4, s4, s88
	v_lshl_add_u64 v[176:177], v[222:223], 0, s[60:61]
	s_mov_b32 m0, s4
	s_nop 0
	global_load_lds_dwordx4 v[176:177], off
	v_lshl_add_u64 v[176:177], v[224:225], 0, s[60:61]
	s_add_i32 m0, s4, 0x2000
	s_nop 0
	global_load_lds_dwordx4 v[176:177], off
	ds_read_b128 v[148:151], v239 offset:49152
	ds_read_b128 v[152:155], v239 offset:50176
	ds_read_b128 v[156:159], v239 offset:51200
	ds_read_b128 v[160:163], v239 offset:52224
	ds_read_b128 v[164:167], v239 offset:53248
	ds_read_b128 v[168:171], v239 offset:54272
	ds_read_b128 v[172:175], v239 offset:55296
	ds_read_b128 v[196:199], v239 offset:56320
	s_waitcnt vmcnt(8)
	s_waitcnt lgkmcnt(0)
	v_mfma_f32_16x16x32_bf16 v[62:65], v[132:135], v[148:151], v[62:65]
	v_mfma_f32_16x16x32_bf16 v[58:61], v[140:143], v[148:151], v[58:61]
	v_mfma_f32_16x16x32_bf16 v[46:49], v[132:135], v[156:159], v[46:49]
	v_mfma_f32_16x16x32_bf16 v[42:45], v[140:143], v[156:159], v[42:45]
	s_barrier
	s_setprio 1
	v_mfma_f32_16x16x32_bf16 v[30:33], v[132:135], v[164:167], v[30:33]
	v_mfma_f32_16x16x32_bf16 v[26:29], v[140:143], v[164:167], v[26:29]
	v_mfma_f32_16x16x32_bf16 v[14:17], v[132:135], v[172:175], v[14:17]
	v_mfma_f32_16x16x32_bf16 v[10:13], v[140:143], v[172:175], v[10:13]
	v_mfma_f32_16x16x32_bf16 v[62:65], v[136:139], v[152:155], v[62:65]
	v_mfma_f32_16x16x32_bf16 v[58:61], v[144:147], v[152:155], v[58:61]
	v_mfma_f32_16x16x32_bf16 v[46:49], v[136:139], v[160:163], v[46:49]
	v_mfma_f32_16x16x32_bf16 v[42:45], v[144:147], v[160:163], v[42:45]
	v_mfma_f32_16x16x32_bf16 v[30:33], v[136:139], v[168:171], v[30:33]
	v_mfma_f32_16x16x32_bf16 v[26:29], v[144:147], v[168:171], v[26:29]
	v_mfma_f32_16x16x32_bf16 v[14:17], v[136:139], v[196:199], v[14:17]
	v_mfma_f32_16x16x32_bf16 v[10:13], v[144:147], v[196:199], v[10:13]
	v_mfma_f32_16x16x32_bf16 v[54:57], v[200:203], v[148:151], v[54:57]
	v_mfma_f32_16x16x32_bf16 v[50:53], v[208:211], v[148:151], v[50:53]
	v_mfma_f32_16x16x32_bf16 v[38:41], v[200:203], v[156:159], v[38:41]
	v_mfma_f32_16x16x32_bf16 v[34:37], v[208:211], v[156:159], v[34:37]
	v_mfma_f32_16x16x32_bf16 v[22:25], v[200:203], v[164:167], v[22:25]
	v_mfma_f32_16x16x32_bf16 v[18:21], v[208:211], v[164:167], v[18:21]
	v_mfma_f32_16x16x32_bf16 v[6:9], v[200:203], v[172:175], v[6:9]
	v_mfma_f32_16x16x32_bf16 v[2:5], v[208:211], v[172:175], v[2:5]
	v_mfma_f32_16x16x32_bf16 v[54:57], v[204:207], v[152:155], v[54:57]
	v_mfma_f32_16x16x32_bf16 v[50:53], v[212:215], v[152:155], v[50:53]
	v_mfma_f32_16x16x32_bf16 v[38:41], v[204:207], v[160:163], v[38:41]
	v_mfma_f32_16x16x32_bf16 v[34:37], v[212:215], v[160:163], v[34:37]
	v_mfma_f32_16x16x32_bf16 v[22:25], v[204:207], v[168:171], v[22:25]
	v_mfma_f32_16x16x32_bf16 v[18:21], v[212:215], v[168:171], v[18:21]
	v_mfma_f32_16x16x32_bf16 v[6:9], v[204:207], v[196:199], v[6:9]
	v_mfma_f32_16x16x32_bf16 v[2:5], v[212:215], v[196:199], v[2:5]
	s_setprio 0
	s_add_u32 s0, s0, 0x100
	s_addc_u32 s1, s1, 0
	s_add_u32 s34, s34, 0x100
	s_addc_u32 s35, s35, 0
	s_cmp_ge_u32 s14, s73
	s_mov_b32 s4, s14
	s_barrier
	s_cbranch_scc0 .LBB0_649
	v_readfirstlane_b32 s98, v219
	s_nop 1
	s_bitcmp1_b32 s98, 8
	s_cbranch_scc1 .Lresync_x_649
	s_barrier

; #define PG8_STAGE(bufoff, gbase, voff) do { _Pragma("unroll") for (int _i = 0; _i < 2; ++_i) \
;         __builtin_amdgcn_global_load_lds((const unsigned*)((const char*)(gbase) + (voff)[_i]), (LAS unsigned*)(lds + (bufoff) + ldsw + _i * 8192), 16, 0, 0); } while (0)
; #define PG8_LDA(dst, b, h) do { _Pragma("unroll") for (int m = 0; m < 4; ++m) _Pragma("unroll") for (int k = 0; k < 2; ++k) dst[m][k] = *(const LAS bf16x8*)(lds + PG8_SA(b, h) + aoff + m * 2048 + k * 1024); } while (0)
; #define PG8_LDB(dst, b, h) do { _Pragma("unroll") for (int n = 0; n < 2; ++n) _Pragma("unroll") for (int k = 0; k < 2; ++k) dst[n][k] = *(const LAS bf16x8*)(lds + PG8_SB(b, h) + boff + n * 2048 + k * 1024); } while (0)
; #define PG8_MMA(ai, bj, At, Bt) do { __builtin_amdgcn_s_setprio(1); _Pragma("unroll") for (int m = 0; m < 4; ++m) _Pragma("unroll") for (int n = 0; n < 2; ++n) _Pragma("unroll") for (int k = 0; k < 2; ++k) \
;         acc[ai][bj][m][n] = __builtin_amdgcn_mfma_f32_16x16x32_bf16(Bt[n][k], At[m][k], acc[ai][bj][m][n], 0, 0, 0); __builtin_amdgcn_s_setprio(0); } while (0)
; #define PG8_WAIT_V(n) asm volatile("s_waitcnt vmcnt(" #n ")" ::: "memory")
; #define PG8_WAIT_L(n) asm volatile("s_waitcnt lgkmcnt(" #n ")" ::: "memory")
; template <class Epi>
; __device__ __forceinline__ void gemm_phase(LAS unsigned char* lds, const Gemm g, const Sched& S, const Epi& E) {
;     ...
;         for (int t = 0; t < nt; t += 2) {
;             const bool last = (t == nt - 2);
;             const char* a1 = cA + (size_t)(t + 1) * kstep;
;             const char* a2 = last ? nA : cA + (size_t)(t + 2) * kstep; const char* b2 = last ? nB : cB + (size_t)(t + 2) * kstep;
;             const char* a3 = a2 + kstep; const char* b3 = b2 + kstep;
;             PG8_LDB(B0, 0, 0); PG8_SCHED; PG8_LDA(At, 0, 0); PG8_STAGE(PG8_SA(1, 1), a1 + hstepA, voffA);
;             PG8_WAIT_L(8); PG8_BAR; PG8_WAIT_L(0); PG8_MMA(0, 0, At, B0); PG8_BAR; PG8_SCHED;
;             PG8_LDB(B1, 0, 1); PG8_STAGE(PG8_SB(0, 0), b2, voffB);
;             PG8_BAR; PG8_WAIT_L(0); PG8_MMA(0, 1, At, B1); PG8_BAR;
;             PG8_LDA(At, 0, 1); PG8_STAGE(PG8_SA(0, 0), a2, voffA);
;             PG8_BAR; PG8_WAIT_L(0); PG8_MMA(1, 0, At, B0); PG8_BAR; PG8_SCHED;
;             PG8_STAGE(PG8_SB(0, 1), b2 + hstepB, voffB);
;             PG8_WAIT_V(6); PG8_BAR; PG8_MMA(1, 1, At, B1); PG8_BAR;
.Lresync_y_825:
.LBB0_825:
	s_add_i32 s86, s68, 2
	s_add_u32 s70, s4, 0x80
	s_addc_u32 s69, s5, 0
	s_cmp_eq_u32 s77, s68
	s_cselect_b32 s68, s59, s70
	s_cselect_b32 s69, s57, s69
	s_cselect_b32 s71, s82, s85
	s_cselect_b32 s70, s83, s84
	v_lshl_add_u64 v[192:193], s[4:5], 0, v[136:137]
	s_add_i32 m0, s33, 0xc000
	s_nop 0
	global_load_lds_dwordx4 v[192:193], off
	v_lshl_add_u64 v[192:193], s[4:5], 0, v[138:139]
	s_add_i32 m0, s33, 0xe000
	s_nop 0
	global_load_lds_dwordx4 v[192:193], off
	s_add_i32 s87, 0, 0x10000
	v_add_u32_e32 v144, s87, v145
	ds_read_b128 v[152:155], v144
	ds_read_b128 v[156:159], v144 offset:1024
	ds_read_b128 v[160:163], v144 offset:2048
	ds_read_b128 v[164:167], v144 offset:3072
	ds_read_b128 v[168:171], v151
	ds_read_b128 v[172:175], v151 offset:1024
	ds_read_b128 v[176:179], v151 offset:2048
	ds_read_b128 v[180:183], v151 offset:3072
	ds_read_b128 v[184:187], v151 offset:4096
	ds_read_b128 v[188:191], v151 offset:5120
	ds_read_b128 v[196:199], v151 offset:6144
	ds_read_b128 v[200:203], v151 offset:7168
	s_add_i32 s88, 0, 0x14000
	v_add_u32_e32 v144, s88, v145
	ds_read_b128 v[204:207], v144
	ds_read_b128 v[208:211], v144 offset:1024
	ds_read_b128 v[212:215], v144 offset:2048
	ds_read_b128 v[234:237], v144 offset:3072
	s_waitcnt vmcnt(8)
	s_waitcnt lgkmcnt(0)
	v_mfma_f32_16x16x32_bf16 v[126:129], v[152:155], v[168:171], v[126:129]
	v_mfma_f32_16x16x32_bf16 v[122:125], v[160:163], v[168:171], v[122:125]
	v_mfma_f32_16x16x32_bf16 v[110:113], v[152:155], v[176:179], v[110:113]
	v_mfma_f32_16x16x32_bf16 v[106:109], v[160:163], v[176:179], v[106:109]
	s_barrier
	s_setprio 1
	v_mfma_f32_16x16x32_bf16 v[94:97], v[152:155], v[184:187], v[94:97]
	v_mfma_f32_16x16x32_bf16 v[90:93], v[160:163], v[184:187], v[90:93]
	v_mfma_f32_16x16x32_bf16 v[78:81], v[152:155], v[196:199], v[78:81]
	v_mfma_f32_16x16x32_bf16 v[74:77], v[160:163], v[196:199], v[74:77]
	v_mfma_f32_16x16x32_bf16 v[126:129], v[156:159], v[172:175], v[126:129]
	v_mfma_f32_16x16x32_bf16 v[122:125], v[164:167], v[172:175], v[122:125]
	v_mfma_f32_16x16x32_bf16 v[110:113], v[156:159], v[180:183], v[110:113]
	v_mfma_f32_16x16x32_bf16 v[106:109], v[164:167], v[180:183], v[106:109]
	v_mfma_f32_16x16x32_bf16 v[94:97], v[156:159], v[188:191], v[94:97]
	v_mfma_f32_16x16x32_bf16 v[90:93], v[164:167], v[188:191], v[90:93]
	v_mfma_f32_16x16x32_bf16 v[78:81], v[156:159], v[200:203], v[78:81]
	v_mfma_f32_16x16x32_bf16 v[74:77], v[164:167], v[200:203], v[74:77]
	v_mfma_f32_16x16x32_bf16 v[118:121], v[204:207], v[168:171], v[118:121]
	v_mfma_f32_16x16x32_bf16 v[114:117], v[212:215], v[168:171], v[114:117]
	v_mfma_f32_16x16x32_bf16 v[102:105], v[204:207], v[176:179], v[102:105]
	v_mfma_f32_16x16x32_bf16 v[98:101], v[212:215], v[176:179], v[98:101]
	v_mfma_f32_16x16x32_bf16 v[86:89], v[204:207], v[184:187], v[86:89]
	v_mfma_f32_16x16x32_bf16 v[82:85], v[212:215], v[184:187], v[82:85]
	v_mfma_f32_16x16x32_bf16 v[70:73], v[204:207], v[196:199], v[70:73]
	v_mfma_f32_16x16x32_bf16 v[66:69], v[212:215], v[196:199], v[66:69]
	v_mfma_f32_16x16x32_bf16 v[118:121], v[208:211], v[172:175], v[118:121]
	v_mfma_f32_16x16x32_bf16 v[114:117], v[234:237], v[172:175], v[114:117]
	v_mfma_f32_16x16x32_bf16 v[102:105], v[208:211], v[180:183], v[102:105]
	v_mfma_f32_16x16x32_bf16 v[98:101], v[234:237], v[180:183], v[98:101]
	v_mfma_f32_16x16x32_bf16 v[86:89], v[208:211], v[188:191], v[86:89]
	v_mfma_f32_16x16x32_bf16 v[82:85], v[234:237], v[188:191], v[82:85]
	v_mfma_f32_16x16x32_bf16 v[70:73], v[208:211], v[200:203], v[70:73]
	v_mfma_f32_16x16x32_bf16 v[66:69], v[234:237], v[200:203], v[66:69]
	s_setprio 0
	s_barrier
	s_add_i32 s87, s87, s51
	v_lshl_add_u64 v[192:193], s[70:71], 0, v[0:1]
	s_mov_b32 m0, s87
	s_nop 0
	global_load_lds_dwordx4 v[192:193], off
	v_lshl_add_u64 v[216:217], s[70:71], 0, v[134:135]
	s_add_i32 m0, s87, 0x2000
	s_nop 0
	global_load_lds_dwordx4 v[216:217], off
	s_mov_b32 m0, s33
	v_lshl_add_u64 v[222:223], s[68:69], 0, v[130:131]
	global_load_lds_dwordx4 v[222:223], off
	v_lshl_add_u64 v[224:225], s[68:69], 0, v[132:133]
	s_mov_b32 m0, s48
	s_nop 0
	global_load_lds_dwordx4 v[224:225], off
	s_add_u32 s70, s70, s14
	s_addc_u32 s71, s71, s15
	s_add_i32 s87, s88, s51
	v_lshl_add_u64 v[226:227], s[70:71], 0, v[0:1]
	s_mov_b32 m0, s87
	v_lshl_add_u64 v[228:229], s[70:71], 0, v[134:135]
	global_load_lds_dwordx4 v[226:227], off
	s_add_i32 m0, s87, 0x2000
	s_nop 0
	global_load_lds_dwordx4 v[228:229], off
	ds_read_b128 v[168:171], v151 offset:16384
	ds_read_b128 v[172:175], v151 offset:17408
	ds_read_b128 v[176:179], v151 offset:18432
	ds_read_b128 v[180:183], v151 offset:19456
	ds_read_b128 v[184:187], v151 offset:20480
	ds_read_b128 v[188:191], v151 offset:21504
	ds_read_b128 v[196:199], v151 offset:22528
	ds_read_b128 v[200:203], v151 offset:23552
	s_waitcnt vmcnt(8)
	s_waitcnt lgkmcnt(0)
	v_mfma_f32_16x16x32_bf16 v[62:65], v[152:155], v[168:171], v[62:65]
	v_mfma_f32_16x16x32_bf16 v[58:61], v[160:163], v[168:171], v[58:61]
	v_mfma_f32_16x16x32_bf16 v[46:49], v[152:155], v[176:179], v[46:49]
	v_mfma_f32_16x16x32_bf16 v[42:45], v[160:163], v[176:179], v[42:45]
	s_barrier
; #define PG8_STAGE(bufoff, gbase, voff) do { _Pragma("unroll") for (int _i = 0; _i < 2; ++_i) \
;         __builtin_amdgcn_global_load_lds((const unsigned*)((const char*)(gbase) + (voff)[_i]), (LAS unsigned*)(lds + (bufoff) + ldsw + _i * 8192), 16, 0, 0); } while (0)
; #define PG8_LDA(dst, b, h) do { _Pragma("unroll") for (int m = 0; m < 4; ++m) _Pragma("unroll") for (int k = 0; k < 2; ++k) dst[m][k] = *(const LAS bf16x8*)(lds + PG8_SA(b, h) + aoff + m * 2048 + k * 1024); } while (0)
; #define PG8_LDB(dst, b, h) do { _Pragma("unroll") for (int n = 0; n < 2; ++n) _Pragma("unroll") for (int k = 0; k < 2; ++k) dst[n][k] = *(const LAS bf16x8*)(lds + PG8_SB(b, h) + boff + n * 2048 + k * 1024); } while (0)
; #define PG8_MMA(ai, bj, At, Bt) do { __builtin_amdgcn_s_setprio(1); _Pragma("unroll") for (int m = 0; m < 4; ++m) _Pragma("unroll") for (int n = 0; n < 2; ++n) _Pragma("unroll") for (int k = 0; k < 2; ++k) \
;         acc[ai][bj][m][n] = __builtin_amdgcn_mfma_f32_16x16x32_bf16(Bt[n][k], At[m][k], acc[ai][bj][m][n], 0, 0, 0); __builtin_amdgcn_s_setprio(0); } while (0)
; #define PG8_WAIT_V(n) asm volatile("s_waitcnt vmcnt(" #n ")" ::: "memory")
; #define PG8_WAIT_L(n) asm volatile("s_waitcnt lgkmcnt(" #n ")" ::: "memory")
; #define PG8_BAR __builtin_amdgcn_s_barrier()
; #define PG8_SCHED __builtin_amdgcn_sched_barrier(0)
; template <class Epi>
; __device__ __forceinline__ void gemm_phase(LAS unsigned char* lds, const Gemm g, const Sched& S, const Epi& E) {
;     ...
;             PG8_BAR; PG8_WAIT_L(0); PG8_MMA(1, 0, At, B0); PG8_BAR; PG8_SCHED;
;             PG8_STAGE(PG8_SB(0, 1), b2 + hstepB, voffB);
;             PG8_WAIT_V(6); PG8_BAR; PG8_MMA(1, 1, At, B1); PG8_BAR;
;             PG8_LDB(B0, 1, 0); PG8_SCHED; PG8_LDA(At, 1, 0); PG8_STAGE(PG8_SA(0, 1), a2 + hstepA, voffA);
;             PG8_WAIT_L(8); PG8_BAR; PG8_WAIT_L(0); PG8_MMA(0, 0, At, B0); PG8_BAR; PG8_SCHED;
;             PG8_LDB(B1, 1, 1); PG8_STAGE(PG8_SB(1, 0), b3, voffB);
;             PG8_BAR; PG8_WAIT_L(0); PG8_MMA(0, 1, At, B1); PG8_BAR;
	s_setprio 1
	v_mfma_f32_16x16x32_bf16 v[30:33], v[152:155], v[184:187], v[30:33]
	v_mfma_f32_16x16x32_bf16 v[26:29], v[160:163], v[184:187], v[26:29]
	v_mfma_f32_16x16x32_bf16 v[14:17], v[152:155], v[196:199], v[14:17]
	v_mfma_f32_16x16x32_bf16 v[10:13], v[160:163], v[196:199], v[10:13]
	v_mfma_f32_16x16x32_bf16 v[62:65], v[156:159], v[172:175], v[62:65]
	v_mfma_f32_16x16x32_bf16 v[58:61], v[164:167], v[172:175], v[58:61]
	v_mfma_f32_16x16x32_bf16 v[46:49], v[156:159], v[180:183], v[46:49]
	v_mfma_f32_16x16x32_bf16 v[42:45], v[164:167], v[180:183], v[42:45]
	v_mfma_f32_16x16x32_bf16 v[30:33], v[156:159], v[188:191], v[30:33]
	v_mfma_f32_16x16x32_bf16 v[26:29], v[164:167], v[188:191], v[26:29]
	v_mfma_f32_16x16x32_bf16 v[14:17], v[156:159], v[200:203], v[14:17]
	v_mfma_f32_16x16x32_bf16 v[10:13], v[164:167], v[200:203], v[10:13]
	v_mfma_f32_16x16x32_bf16 v[54:57], v[204:207], v[168:171], v[54:57]
	v_mfma_f32_16x16x32_bf16 v[50:53], v[212:215], v[168:171], v[50:53]
	v_mfma_f32_16x16x32_bf16 v[38:41], v[204:207], v[176:179], v[38:41]
	v_mfma_f32_16x16x32_bf16 v[34:37], v[212:215], v[176:179], v[34:37]
	v_mfma_f32_16x16x32_bf16 v[22:25], v[204:207], v[184:187], v[22:25]
	v_mfma_f32_16x16x32_bf16 v[18:21], v[212:215], v[184:187], v[18:21]
	v_mfma_f32_16x16x32_bf16 v[6:9], v[204:207], v[196:199], v[6:9]
	v_mfma_f32_16x16x32_bf16 v[2:5], v[212:215], v[196:199], v[2:5]
	v_mfma_f32_16x16x32_bf16 v[54:57], v[208:211], v[172:175], v[54:57]
	v_mfma_f32_16x16x32_bf16 v[50:53], v[234:237], v[172:175], v[50:53]
	v_mfma_f32_16x16x32_bf16 v[38:41], v[208:211], v[180:183], v[38:41]
	v_mfma_f32_16x16x32_bf16 v[34:37], v[234:237], v[180:183], v[34:37]
	v_mfma_f32_16x16x32_bf16 v[22:25], v[208:211], v[188:191], v[22:25]
	v_mfma_f32_16x16x32_bf16 v[18:21], v[234:237], v[188:191], v[18:21]
	v_mfma_f32_16x16x32_bf16 v[6:9], v[208:211], v[200:203], v[6:9]
	v_mfma_f32_16x16x32_bf16 v[2:5], v[234:237], v[200:203], v[2:5]
	s_setprio 0
	s_barrier
	s_add_u32 s68, s68, s6
	s_addc_u32 s69, s69, s7
	s_mov_b32 m0, s58
	v_lshl_add_u64 v[204:205], s[68:69], 0, v[130:131]
	global_load_lds_dwordx4 v[204:205], off
	v_lshl_add_u64 v[204:205], s[68:69], 0, v[132:133]
	s_mov_b32 m0, s72
	s_nop 0
	global_load_lds_dwordx4 v[204:205], off
	s_add_i32 s70, 0, 0x18000
	v_add_u32_e32 v144, s70, v145
	ds_read_b128 v[152:155], v144
	ds_read_b128 v[156:159], v144 offset:1024
	ds_read_b128 v[160:163], v144 offset:2048
	ds_read_b128 v[164:167], v144 offset:3072
	ds_read_b128 v[168:171], v151 offset:32768
	ds_read_b128 v[172:175], v151 offset:33792
	ds_read_b128 v[176:179], v151 offset:34816
	ds_read_b128 v[180:183], v151 offset:35840
	ds_read_b128 v[184:187], v151 offset:36864
	ds_read_b128 v[188:191], v151 offset:37888
	ds_read_b128 v[196:199], v151 offset:38912
	ds_read_b128 v[200:203], v151 offset:39936
	s_add_i32 s68, 0, 0x1c000
	v_add_u32_e32 v144, s68, v145
	ds_read_b128 v[204:207], v144
	ds_read_b128 v[208:211], v144 offset:1024
	ds_read_b128 v[212:215], v144 offset:2048
	ds_read_b128 v[234:237], v144 offset:3072
	s_waitcnt vmcnt(8)
	s_waitcnt lgkmcnt(0)
	v_mfma_f32_16x16x32_bf16 v[126:129], v[152:155], v[168:171], v[126:129]
	v_mfma_f32_16x16x32_bf16 v[122:125], v[160:163], v[168:171], v[122:125]
	v_mfma_f32_16x16x32_bf16 v[110:113], v[152:155], v[176:179], v[110:113]
	v_mfma_f32_16x16x32_bf16 v[106:109], v[160:163], v[176:179], v[106:109]
	s_barrier
	s_setprio 1
	v_mfma_f32_16x16x32_bf16 v[94:97], v[152:155], v[184:187], v[94:97]
	v_mfma_f32_16x16x32_bf16 v[90:93], v[160:163], v[184:187], v[90:93]
	v_mfma_f32_16x16x32_bf16 v[78:81], v[152:155], v[196:199], v[78:81]
	v_mfma_f32_16x16x32_bf16 v[74:77], v[160:163], v[196:199], v[74:77]
	v_mfma_f32_16x16x32_bf16 v[126:129], v[156:159], v[172:175], v[126:129]
	v_mfma_f32_16x16x32_bf16 v[122:125], v[164:167], v[172:175], v[122:125]
	v_mfma_f32_16x16x32_bf16 v[110:113], v[156:159], v[180:183], v[110:113]
	v_mfma_f32_16x16x32_bf16 v[106:109], v[164:167], v[180:183], v[106:109]
	v_mfma_f32_16x16x32_bf16 v[94:97], v[156:159], v[188:191], v[94:97]
	v_mfma_f32_16x16x32_bf16 v[90:93], v[164:167], v[188:191], v[90:93]
	v_mfma_f32_16x16x32_bf16 v[78:81], v[156:159], v[200:203], v[78:81]
	v_mfma_f32_16x16x32_bf16 v[74:77], v[164:167], v[200:203], v[74:77]
	v_mfma_f32_16x16x32_bf16 v[118:121], v[204:207], v[168:171], v[118:121]
	v_mfma_f32_16x16x32_bf16 v[114:117], v[212:215], v[168:171], v[114:117]
	v_mfma_f32_16x16x32_bf16 v[102:105], v[204:207], v[176:179], v[102:105]
	v_mfma_f32_16x16x32_bf16 v[98:101], v[212:215], v[176:179], v[98:101]
	v_mfma_f32_16x16x32_bf16 v[86:89], v[204:207], v[184:187], v[86:89]
	v_mfma_f32_16x16x32_bf16 v[82:85], v[212:215], v[184:187], v[82:85]
	v_mfma_f32_16x16x32_bf16 v[70:73], v[204:207], v[196:199], v[70:73]
	v_mfma_f32_16x16x32_bf16 v[66:69], v[212:215], v[196:199], v[66:69]
	v_mfma_f32_16x16x32_bf16 v[118:121], v[208:211], v[172:175], v[118:121]
	v_mfma_f32_16x16x32_bf16 v[114:117], v[234:237], v[172:175], v[114:117]
	v_mfma_f32_16x16x32_bf16 v[102:105], v[208:211], v[180:183], v[102:105]
	v_mfma_f32_16x16x32_bf16 v[98:101], v[234:237], v[180:183], v[98:101]
	v_mfma_f32_16x16x32_bf16 v[86:89], v[208:211], v[188:191], v[86:89]
	v_mfma_f32_16x16x32_bf16 v[82:85], v[234:237], v[188:191], v[82:85]
	v_mfma_f32_16x16x32_bf16 v[70:73], v[208:211], v[200:203], v[70:73]
	v_mfma_f32_16x16x32_bf16 v[66:69], v[234:237], v[200:203], v[66:69]
	s_setprio 0
	s_barrier
; #define PG8_STAGE(bufoff, gbase, voff) do { _Pragma("unroll") for (int _i = 0; _i < 2; ++_i) \
;         __builtin_amdgcn_global_load_lds((const unsigned*)((const char*)(gbase) + (voff)[_i]), (LAS unsigned*)(lds + (bufoff) + ldsw + _i * 8192), 16, 0, 0); } while (0)
; #define PG8_LDA(dst, b, h) do { _Pragma("unroll") for (int m = 0; m < 4; ++m) _Pragma("unroll") for (int k = 0; k < 2; ++k) dst[m][k] = *(const LAS bf16x8*)(lds + PG8_SA(b, h) + aoff + m * 2048 + k * 1024); } while (0)
; #define PG8_MMA(ai, bj, At, Bt) do { __builtin_amdgcn_s_setprio(1); _Pragma("unroll") for (int m = 0; m < 4; ++m) _Pragma("unroll") for (int n = 0; n < 2; ++n) _Pragma("unroll") for (int k = 0; k < 2; ++k) \
;         acc[ai][bj][m][n] = __builtin_amdgcn_mfma_f32_16x16x32_bf16(Bt[n][k], At[m][k], acc[ai][bj][m][n], 0, 0, 0); __builtin_amdgcn_s_setprio(0); } while (0)
; #define PG8_WAIT_V(n) asm volatile("s_waitcnt vmcnt(" #n ")" ::: "memory")
; #define PG8_WAIT_L(n) asm volatile("s_waitcnt lgkmcnt(" #n ")" ::: "memory")
; #define PG8_BAR __builtin_amdgcn_s_barrier()
; #define PG8_SCHED __builtin_amdgcn_sched_barrier(0)
; template <class Epi>
; __device__ __forceinline__ void gemm_phase(LAS unsigned char* lds, const Gemm g, const Sched& S, const Epi& E) {
;     ...
;             PG8_LDA(At, 1, 1); PG8_STAGE(PG8_SA(1, 0), a3, voffA);
;             PG8_BAR; PG8_WAIT_L(0); PG8_MMA(1, 0, At, B0); PG8_BAR; PG8_SCHED;
;             PG8_STAGE(PG8_SB(1, 1), b3 + hstepB, voffB);
;             PG8_WAIT_V(6); PG8_BAR; PG8_MMA(1, 1, At, B1); PG8_BAR;
;         }
	s_add_i32 s69, s70, s51
	v_lshl_add_u64 v[192:193], v[192:193], 0, s[60:61]
	s_mov_b32 m0, s69
	s_nop 0
	global_load_lds_dwordx4 v[192:193], off
	v_lshl_add_u64 v[192:193], v[216:217], 0, s[60:61]
	s_add_i32 m0, s69, 0x2000
	s_nop 0
	global_load_lds_dwordx4 v[192:193], off
	s_mov_b32 m0, s75
	v_lshl_add_u64 v[192:193], v[222:223], 0, s[60:61]
	global_load_lds_dwordx4 v[192:193], off
	v_lshl_add_u64 v[192:193], v[224:225], 0, s[60:61]
	s_mov_b32 m0, s76
	s_nop 0
	global_load_lds_dwordx4 v[192:193], off
	s_add_i32 s68, s68, s51
	v_lshl_add_u64 v[192:193], v[226:227], 0, s[60:61]
	s_mov_b32 m0, s68
	s_nop 0
	global_load_lds_dwordx4 v[192:193], off
	v_lshl_add_u64 v[192:193], v[228:229], 0, s[60:61]
	s_add_i32 m0, s68, 0x2000
	s_nop 0
	global_load_lds_dwordx4 v[192:193], off
	ds_read_b128 v[168:171], v151 offset:49152
	ds_read_b128 v[172:175], v151 offset:50176
	ds_read_b128 v[176:179], v151 offset:51200
	ds_read_b128 v[180:183], v151 offset:52224
	ds_read_b128 v[184:187], v151 offset:53248
	ds_read_b128 v[188:191], v151 offset:54272
	ds_read_b128 v[196:199], v151 offset:55296
	ds_read_b128 v[200:203], v151 offset:56320
	s_waitcnt vmcnt(8)
	s_waitcnt lgkmcnt(0)
	v_mfma_f32_16x16x32_bf16 v[62:65], v[152:155], v[168:171], v[62:65]
	v_mfma_f32_16x16x32_bf16 v[58:61], v[160:163], v[168:171], v[58:61]
	v_mfma_f32_16x16x32_bf16 v[46:49], v[152:155], v[176:179], v[46:49]
	v_mfma_f32_16x16x32_bf16 v[42:45], v[160:163], v[176:179], v[42:45]
	s_barrier
	s_setprio 1
	v_mfma_f32_16x16x32_bf16 v[30:33], v[152:155], v[184:187], v[30:33]
	v_mfma_f32_16x16x32_bf16 v[26:29], v[160:163], v[184:187], v[26:29]
	v_mfma_f32_16x16x32_bf16 v[14:17], v[152:155], v[196:199], v[14:17]
	v_mfma_f32_16x16x32_bf16 v[10:13], v[160:163], v[196:199], v[10:13]
	v_mfma_f32_16x16x32_bf16 v[62:65], v[156:159], v[172:175], v[62:65]
	v_mfma_f32_16x16x32_bf16 v[58:61], v[164:167], v[172:175], v[58:61]
	v_mfma_f32_16x16x32_bf16 v[46:49], v[156:159], v[180:183], v[46:49]
	v_mfma_f32_16x16x32_bf16 v[42:45], v[164:167], v[180:183], v[42:45]
	v_mfma_f32_16x16x32_bf16 v[30:33], v[156:159], v[188:191], v[30:33]
	v_mfma_f32_16x16x32_bf16 v[26:29], v[164:167], v[188:191], v[26:29]
	v_mfma_f32_16x16x32_bf16 v[14:17], v[156:159], v[200:203], v[14:17]
	v_mfma_f32_16x16x32_bf16 v[10:13], v[164:167], v[200:203], v[10:13]
	v_mfma_f32_16x16x32_bf16 v[54:57], v[204:207], v[168:171], v[54:57]
	v_mfma_f32_16x16x32_bf16 v[50:53], v[212:215], v[168:171], v[50:53]
	v_mfma_f32_16x16x32_bf16 v[38:41], v[204:207], v[176:179], v[38:41]
	v_mfma_f32_16x16x32_bf16 v[34:37], v[212:215], v[176:179], v[34:37]
	v_mfma_f32_16x16x32_bf16 v[22:25], v[204:207], v[184:187], v[22:25]
	v_mfma_f32_16x16x32_bf16 v[18:21], v[212:215], v[184:187], v[18:21]
	v_mfma_f32_16x16x32_bf16 v[6:9], v[204:207], v[196:199], v[6:9]
	v_mfma_f32_16x16x32_bf16 v[2:5], v[212:215], v[196:199], v[2:5]
	v_mfma_f32_16x16x32_bf16 v[54:57], v[208:211], v[172:175], v[54:57]
	v_mfma_f32_16x16x32_bf16 v[50:53], v[234:237], v[172:175], v[50:53]
	v_mfma_f32_16x16x32_bf16 v[38:41], v[208:211], v[180:183], v[38:41]
	v_mfma_f32_16x16x32_bf16 v[34:37], v[234:237], v[180:183], v[34:37]
	v_mfma_f32_16x16x32_bf16 v[22:25], v[208:211], v[188:191], v[22:25]
	v_mfma_f32_16x16x32_bf16 v[18:21], v[234:237], v[188:191], v[18:21]
	v_mfma_f32_16x16x32_bf16 v[6:9], v[208:211], v[200:203], v[6:9]
	v_mfma_f32_16x16x32_bf16 v[2:5], v[234:237], v[200:203], v[2:5]
	s_setprio 0
	s_add_u32 s4, s4, 0x100
	s_addc_u32 s5, s5, 0
	s_add_u32 s84, s84, 0x100
	s_addc_u32 s85, s85, 0
	s_cmp_ge_u32 s86, s73
	s_mov_b32 s68, s86
	s_barrier
	s_cbranch_scc0 .LBB0_825
	v_readfirstlane_b32 s98, v219
	s_nop 1
	s_bitcmp1_b32 s98, 8
	s_cbranch_scc1 .Lresync_x_825
	s_barrier
